# adds software-pipelined K loop to the merge-phase gate GEMM
# speedup vs baseline: 1.0781x; 1.0067x over previous
;     ...
;   for (int kt = 0; kt < nk; ++kt) {
;     if (kt + 1 < nk) asm volatile("s_waitcnt vmcnt(6)" ::: "memory");
;     else asm volatile("s_waitcnt vmcnt(0)" ::: "memory");
;     __builtin_amdgcn_s_barrier();
;     asm volatile("" ::: "memory");
;     if (kt + 2 < nk) { const int st2 = (st >= 1) ? st - 1 : 2; GEMM_ISSUE(kt + 2, st2); }
;     const char* la = lds + st * STAGE_B;
;     const char* lb = la + 32768;
;     const unsigned sa_u = (unsigned)(size_t)la + arow_u, sb_u = (unsigned)(size_t)lb + brow_u;
;     const unsigned a0 = sa_u + co0, a1 = sa_u + co1, a2 = sa_u + co2, a3 = sa_u + co3;
;     const unsigned b0 = sb_u + co0, b1 = sb_u + co1, b2 = sb_u + co2, b3 = sb_u + co3;
;     {
;       bf16x8 p0, p1, q0, q1, u0, u1, w0, w1;
;       asm volatile(
;         "ds_read_b128 %4, %12\n\tds_read_b128 %5, %12 offset:4096\n\tds_read_b128 %6, %16\n\tds_read_b128 %7, %16 offset:4096\n\t"
;         "ds_read_b128 %8, %13\n\tds_read_b128 %9, %13 offset:4096\n\tds_read_b128 %10, %17\n\tds_read_b128 %11, %17 offset:4096\n\t"
;         "s_waitcnt lgkmcnt(4)\n\t"
;         "v_mfma_f32_32x32x16_bf16 %0, %4, %6, %0\n\tv_mfma_f32_32x32x16_bf16 %1, %4, %7, %1\n\tv_mfma_f32_32x32x16_bf16 %2, %5, %6, %2\n\tv_mfma_f32_32x32x16_bf16 %3, %5, %7, %3\n\t"
;         "ds_read_b128 %4, %14\n\tds_read_b128 %5, %14 offset:4096\n\tds_read_b128 %6, %18\n\tds_read_b128 %7, %18 offset:4096\n\t"
;         "s_waitcnt lgkmcnt(4)\n\t"
;         "v_mfma_f32_32x32x16_bf16 %0, %8, %10, %0\n\tv_mfma_f32_32x32x16_bf16 %1, %8, %11, %1\n\tv_mfma_f32_32x32x16_bf16 %2, %9, %10, %2\n\tv_mfma_f32_32x32x16_bf16 %3, %9, %11, %3\n\t"
;         "ds_read_b128 %8, %15\n\tds_read_b128 %9, %15 offset:4096\n\tds_read_b128 %10, %19\n\tds_read_b128 %11, %19 offset:4096\n\t"
;         "s_waitcnt lgkmcnt(4)\n\t"
;         "v_mfma_f32_32x32x16_bf16 %0, %4, %6, %0\n\tv_mfma_f32_32x32x16_bf16 %1, %4, %7, %1\n\tv_mfma_f32_32x32x16_bf16 %2, %5, %6, %2\n\tv_mfma_f32_32x32x16_bf16 %3, %5, %7, %3\n\t"
;         "s_waitcnt lgkmcnt(0)\n\t"
;         "v_mfma_f32_32x32x16_bf16 %0, %8, %10, %0\n\tv_mfma_f32_32x32x16_bf16 %1, %8, %11, %1\n\tv_mfma_f32_32x32x16_bf16 %2, %9, %10, %2\n\tv_mfma_f32_32x32x16_bf16 %3, %9, %11, %3"
;         : "+v"(acc[0][0]), "+v"(acc[0][1]), "+v"(acc[1][0]), "+v"(acc[1][1]),
;           "=&v"(p0), "=&v"(p1), "=&v"(q0), "=&v"(q1), "=&v"(u0), "=&v"(u1), "=&v"(w0), "=&v"(w1)
.LBB0_106:
	v_and_b32_e32 v164, 31, v129
	v_bfe_u32 v165, v129, 5, 1
	v_lshrrev_b32_e32 v166, 6, v129
	v_bfe_u32 v168, v129, 1, 3
	v_lshrrev_b32_e32 v167, 1, v166
	v_and_b32_e32 v166, 1, v166
	v_xor_b32_e32 v165, v165, v168
	v_lshl_add_u32 v167, v167, 6, v164
	v_lshl_add_u32 v166, v166, 6, v164
	v_lshlrev_b32_e32 v165, 4, v165
	v_lshlrev_b32_e32 v167, 7, v167
	v_lshlrev_b32_e32 v166, 7, v166
	v_add_u32_e32 v166, 0x8000, v166
	v_add_u32_e32 v144, v167, v165
	v_add_u32_e32 v148, v166, v165
	v_xor_b32_e32 v169, 0x20, v165
	v_add_u32_e32 v145, v167, v169
	v_add_u32_e32 v149, v166, v169
	v_xor_b32_e32 v169, 0x40, v165
	v_add_u32_e32 v146, v167, v169
	v_add_u32_e32 v150, v166, v169
	v_xor_b32_e32 v169, 0x60, v165
	v_add_u32_e32 v147, v167, v169
	v_add_u32_e32 v151, v166, v169
	v_add_u32_e32 v152, 0x18000, v144
	v_add_u32_e32 v157, 0x18000, v148
	v_add_u32_e32 v153, 0x18000, v145
	v_add_u32_e32 v158, 0x18000, v149
	v_add_u32_e32 v154, 0x18000, v146
	v_add_u32_e32 v159, 0x18000, v150
	v_add_u32_e32 v155, 0x18000, v147
	v_add_u32_e32 v160, 0x18000, v151
	v_lshlrev_b32_e32 v164, 4, v129
	s_nop 0
	v_readfirstlane_b32 s25, v164
	s_mov_b32 s65, 0
	s_waitcnt vmcnt(6)
	s_barrier
	ds_read_b128 v[164:167], v144
	ds_read_b128 v[168:171], v144 offset:4096
	ds_read_b128 v[172:175], v148
	ds_read_b128 v[176:179], v148 offset:4096
	s_mov_b32 s64, 0x65c2100
	s_add_u32 m0, s25, 0x18000
	v_lshl_add_u64 v[226:227], v[142:143], 0, s[64:65]
	global_load_lds_dwordx4 v[226:227], off
	s_add_u32 m0, s25, 0x1a000
	v_lshl_add_u64 v[228:229], v[140:141], 0, s[64:65]
	global_load_lds_dwordx4 v[228:229], off
	ds_read_b128 v[180:183], v145
	ds_read_b128 v[184:187], v145 offset:4096
	ds_read_b128 v[218:221], v149
	ds_read_b128 v[222:225], v149 offset:4096
	s_waitcnt lgkmcnt(4)
	v_mfma_f32_32x32x16_bf16 v[48:63], v[164:167], v[172:175], v[48:63]
	s_add_u32 m0, s25, 0x1c000
	v_lshl_add_u64 v[226:227], v[138:139], 0, s[64:65]
	global_load_lds_dwordx4 v[226:227], off
	v_mfma_f32_32x32x16_bf16 v[32:47], v[164:167], v[176:179], v[32:47]
	v_mfma_f32_32x32x16_bf16 v[16:31], v[168:171], v[172:175], v[16:31]
	s_add_u32 m0, s25, 0x1e000
	v_lshl_add_u64 v[228:229], v[136:137], 0, s[64:65]
	global_load_lds_dwordx4 v[228:229], off
	v_mfma_f32_32x32x16_bf16 v[0:15], v[168:171], v[176:179], v[0:15]
	ds_read_b128 v[164:167], v146
	ds_read_b128 v[168:171], v146 offset:4096
	ds_read_b128 v[172:175], v150
	ds_read_b128 v[176:179], v150 offset:4096
	s_waitcnt lgkmcnt(4)
	v_mfma_f32_32x32x16_bf16 v[48:63], v[180:183], v[218:221], v[48:63]
	s_mov_b32 s64, 0x2740100
	s_add_u32 m0, s25, 0x20000
	v_lshl_add_u64 v[226:227], v[134:135], 0, s[64:65]
	global_load_lds_dwordx4 v[226:227], off
	v_mfma_f32_32x32x16_bf16 v[32:47], v[180:183], v[222:225], v[32:47]
	v_mfma_f32_32x32x16_bf16 v[16:31], v[184:187], v[218:221], v[16:31]
	s_add_u32 m0, s25, 0x22000
	v_lshl_add_u64 v[228:229], v[132:133], 0, s[64:65]
	global_load_lds_dwordx4 v[228:229], off
	v_mfma_f32_32x32x16_bf16 v[0:15], v[184:187], v[222:225], v[0:15]
	ds_read_b128 v[180:183], v147
	ds_read_b128 v[184:187], v147 offset:4096
	ds_read_b128 v[218:221], v151
	ds_read_b128 v[222:225], v151 offset:4096
	s_waitcnt lgkmcnt(4)
	v_mfma_f32_32x32x16_bf16 v[48:63], v[164:167], v[172:175], v[48:63]
	v_mfma_f32_32x32x16_bf16 v[32:47], v[164:167], v[176:179], v[32:47]
	v_mfma_f32_32x32x16_bf16 v[16:31], v[168:171], v[172:175], v[16:31]
	v_mfma_f32_32x32x16_bf16 v[0:15], v[168:171], v[176:179], v[0:15]
	s_waitcnt vmcnt(6) lgkmcnt(0)
	s_barrier
	ds_read_b128 v[164:167], v144 offset:49152
	ds_read_b128 v[168:171], v144 offset:53248
	ds_read_b128 v[172:175], v148 offset:49152
	ds_read_b128 v[176:179], v148 offset:53248
	v_mfma_f32_32x32x16_bf16 v[48:63], v[180:183], v[218:221], v[48:63]
	s_mov_b32 s64, 0x65c2180
	s_mov_b32 m0, s25
	v_lshl_add_u64 v[226:227], v[142:143], 0, s[64:65]
	global_load_lds_dwordx4 v[226:227], off
	v_mfma_f32_32x32x16_bf16 v[32:47], v[180:183], v[222:225], v[32:47]
	v_mfma_f32_32x32x16_bf16 v[16:31], v[184:187], v[218:221], v[16:31]
	s_add_u32 m0, s25, 0x2000
	v_lshl_add_u64 v[228:229], v[140:141], 0, s[64:65]
	global_load_lds_dwordx4 v[228:229], off
	v_mfma_f32_32x32x16_bf16 v[0:15], v[184:187], v[222:225], v[0:15]
	ds_read_b128 v[180:183], v145 offset:49152
	ds_read_b128 v[184:187], v145 offset:53248
	ds_read_b128 v[218:221], v149 offset:49152
	ds_read_b128 v[222:225], v149 offset:53248
	s_waitcnt lgkmcnt(4)
	v_mfma_f32_32x32x16_bf16 v[48:63], v[164:167], v[172:175], v[48:63]
	s_add_u32 m0, s25, 0x4000
	v_lshl_add_u64 v[226:227], v[138:139], 0, s[64:65]
	global_load_lds_dwordx4 v[226:227], off
	v_mfma_f32_32x32x16_bf16 v[32:47], v[164:167], v[176:179], v[32:47]
	v_mfma_f32_32x32x16_bf16 v[16:31], v[168:171], v[172:175], v[16:31]
	s_add_u32 m0, s25, 0x6000
	v_lshl_add_u64 v[228:229], v[136:137], 0, s[64:65]
	global_load_lds_dwordx4 v[228:229], off
	v_mfma_f32_32x32x16_bf16 v[0:15], v[168:171], v[176:179], v[0:15]
	ds_read_b128 v[164:167], v146 offset:49152
	ds_read_b128 v[168:171], v146 offset:53248
	ds_read_b128 v[172:175], v150 offset:49152
	ds_read_b128 v[176:179], v150 offset:53248
	s_waitcnt lgkmcnt(4)
	v_mfma_f32_32x32x16_bf16 v[48:63], v[180:183], v[218:221], v[48:63]
	s_mov_b32 s64, 0x2740180
	s_add_u32 m0, s25, 0x8000
	v_lshl_add_u64 v[226:227], v[134:135], 0, s[64:65]
	global_load_lds_dwordx4 v[226:227], off
	v_mfma_f32_32x32x16_bf16 v[32:47], v[180:183], v[222:225], v[32:47]
	v_mfma_f32_32x32x16_bf16 v[16:31], v[184:187], v[218:221], v[16:31]
	s_add_u32 m0, s25, 0xa000
	v_lshl_add_u64 v[228:229], v[132:133], 0, s[64:65]
	global_load_lds_dwordx4 v[228:229], off
	v_mfma_f32_32x32x16_bf16 v[0:15], v[184:187], v[222:225], v[0:15]
	ds_read_b128 v[180:183], v147 offset:49152
	ds_read_b128 v[184:187], v147 offset:53248
	ds_read_b128 v[218:221], v151 offset:49152
	ds_read_b128 v[222:225], v151 offset:53248
	s_waitcnt lgkmcnt(4)
	v_mfma_f32_32x32x16_bf16 v[48:63], v[164:167], v[172:175], v[48:63]
	v_mfma_f32_32x32x16_bf16 v[32:47], v[164:167], v[176:179], v[32:47]
	v_mfma_f32_32x32x16_bf16 v[16:31], v[168:171], v[172:175], v[16:31]
	v_mfma_f32_32x32x16_bf16 v[0:15], v[168:171], v[176:179], v[0:15]
	s_waitcnt vmcnt(6) lgkmcnt(0)
	s_barrier
;     ...
;   for (int kt = 0; kt < nk; ++kt) {
;     if (kt + 1 < nk) asm volatile("s_waitcnt vmcnt(6)" ::: "memory");
;     else asm volatile("s_waitcnt vmcnt(0)" ::: "memory");
;     __builtin_amdgcn_s_barrier();
;     asm volatile("" ::: "memory");
;     if (kt + 2 < nk) { const int st2 = (st >= 1) ? st - 1 : 2; GEMM_ISSUE(kt + 2, st2); }
;     const char* la = lds + st * STAGE_B;
;     const char* lb = la + 32768;
;     const unsigned sa_u = (unsigned)(size_t)la + arow_u, sb_u = (unsigned)(size_t)lb + brow_u;
;     const unsigned a0 = sa_u + co0, a1 = sa_u + co1, a2 = sa_u + co2, a3 = sa_u + co3;
;     const unsigned b0 = sb_u + co0, b1 = sb_u + co1, b2 = sb_u + co2, b3 = sb_u + co3;
;     {
;       bf16x8 p0, p1, q0, q1, u0, u1, w0, w1;
;       asm volatile(
;         "ds_read_b128 %4, %12\n\tds_read_b128 %5, %12 offset:4096\n\tds_read_b128 %6, %16\n\tds_read_b128 %7, %16 offset:4096\n\t"
;         "ds_read_b128 %8, %13\n\tds_read_b128 %9, %13 offset:4096\n\tds_read_b128 %10, %17\n\tds_read_b128 %11, %17 offset:4096\n\t"
;         "s_waitcnt lgkmcnt(4)\n\t"
;         "v_mfma_f32_32x32x16_bf16 %0, %4, %6, %0\n\tv_mfma_f32_32x32x16_bf16 %1, %4, %7, %1\n\tv_mfma_f32_32x32x16_bf16 %2, %5, %6, %2\n\tv_mfma_f32_32x32x16_bf16 %3, %5, %7, %3\n\t"
;         "ds_read_b128 %4, %14\n\tds_read_b128 %5, %14 offset:4096\n\tds_read_b128 %6, %18\n\tds_read_b128 %7, %18 offset:4096\n\t"
;         "s_waitcnt lgkmcnt(4)\n\t"
;         "v_mfma_f32_32x32x16_bf16 %0, %8, %10, %0\n\tv_mfma_f32_32x32x16_bf16 %1, %8, %11, %1\n\tv_mfma_f32_32x32x16_bf16 %2, %9, %10, %2\n\tv_mfma_f32_32x32x16_bf16 %3, %9, %11, %3\n\t"
;         "ds_read_b128 %8, %15\n\tds_read_b128 %9, %15 offset:4096\n\tds_read_b128 %10, %19\n\tds_read_b128 %11, %19 offset:4096\n\t"
;         "s_waitcnt lgkmcnt(4)\n\t"
;         "v_mfma_f32_32x32x16_bf16 %0, %4, %6, %0\n\tv_mfma_f32_32x32x16_bf16 %1, %4, %7, %1\n\tv_mfma_f32_32x32x16_bf16 %2, %5, %6, %2\n\tv_mfma_f32_32x32x16_bf16 %3, %5, %7, %3\n\t"
;         "s_waitcnt lgkmcnt(0)\n\t"
;         "v_mfma_f32_32x32x16_bf16 %0, %8, %10, %0\n\tv_mfma_f32_32x32x16_bf16 %1, %8, %11, %1\n\tv_mfma_f32_32x32x16_bf16 %2, %9, %10, %2\n\tv_mfma_f32_32x32x16_bf16 %3, %9, %11, %3"
;         : "+v"(acc[0][0]), "+v"(acc[0][1]), "+v"(acc[1][0]), "+v"(acc[1][1]),
;           "=&v"(p0), "=&v"(p1), "=&v"(q0), "=&v"(q1), "=&v"(u0), "=&v"(u1), "=&v"(w0), "=&v"(w1)
	ds_read_b128 v[164:167], v152
	ds_read_b128 v[168:171], v152 offset:4096
	ds_read_b128 v[172:175], v157
	ds_read_b128 v[176:179], v157 offset:4096
	v_mfma_f32_32x32x16_bf16 v[48:63], v[180:183], v[218:221], v[48:63]
	s_mov_b32 s64, 0x65c2200
	s_add_u32 m0, s25, 0xc000
	v_lshl_add_u64 v[226:227], v[142:143], 0, s[64:65]
	global_load_lds_dwordx4 v[226:227], off
	v_mfma_f32_32x32x16_bf16 v[32:47], v[180:183], v[222:225], v[32:47]
	v_mfma_f32_32x32x16_bf16 v[16:31], v[184:187], v[218:221], v[16:31]
	s_add_u32 m0, s25, 0xe000
	v_lshl_add_u64 v[228:229], v[140:141], 0, s[64:65]
	global_load_lds_dwordx4 v[228:229], off
	v_mfma_f32_32x32x16_bf16 v[0:15], v[184:187], v[222:225], v[0:15]
	ds_read_b128 v[180:183], v153
	ds_read_b128 v[184:187], v153 offset:4096
	ds_read_b128 v[218:221], v158
	ds_read_b128 v[222:225], v158 offset:4096
	s_waitcnt lgkmcnt(4)
	v_mfma_f32_32x32x16_bf16 v[48:63], v[164:167], v[172:175], v[48:63]
	s_add_u32 m0, s25, 0x10000
	v_lshl_add_u64 v[226:227], v[138:139], 0, s[64:65]
	global_load_lds_dwordx4 v[226:227], off
	v_mfma_f32_32x32x16_bf16 v[32:47], v[164:167], v[176:179], v[32:47]
	v_mfma_f32_32x32x16_bf16 v[16:31], v[168:171], v[172:175], v[16:31]
	s_add_u32 m0, s25, 0x12000
	v_lshl_add_u64 v[228:229], v[136:137], 0, s[64:65]
	global_load_lds_dwordx4 v[228:229], off
	v_mfma_f32_32x32x16_bf16 v[0:15], v[168:171], v[176:179], v[0:15]
	ds_read_b128 v[164:167], v154
	ds_read_b128 v[168:171], v154 offset:4096
	ds_read_b128 v[172:175], v159
	ds_read_b128 v[176:179], v159 offset:4096
	s_waitcnt lgkmcnt(4)
	v_mfma_f32_32x32x16_bf16 v[48:63], v[180:183], v[218:221], v[48:63]
	s_mov_b32 s64, 0x2740200
	s_add_u32 m0, s25, 0x14000
	v_lshl_add_u64 v[226:227], v[134:135], 0, s[64:65]
	global_load_lds_dwordx4 v[226:227], off
	v_mfma_f32_32x32x16_bf16 v[32:47], v[180:183], v[222:225], v[32:47]
	v_mfma_f32_32x32x16_bf16 v[16:31], v[184:187], v[218:221], v[16:31]
	s_add_u32 m0, s25, 0x16000
	v_lshl_add_u64 v[228:229], v[132:133], 0, s[64:65]
	global_load_lds_dwordx4 v[228:229], off
	v_mfma_f32_32x32x16_bf16 v[0:15], v[184:187], v[222:225], v[0:15]
	ds_read_b128 v[180:183], v155
	ds_read_b128 v[184:187], v155 offset:4096
	ds_read_b128 v[218:221], v160
	ds_read_b128 v[222:225], v160 offset:4096
	s_waitcnt lgkmcnt(4)
	v_mfma_f32_32x32x16_bf16 v[48:63], v[164:167], v[172:175], v[48:63]
	v_mfma_f32_32x32x16_bf16 v[32:47], v[164:167], v[176:179], v[32:47]
	v_mfma_f32_32x32x16_bf16 v[16:31], v[168:171], v[172:175], v[16:31]
	v_mfma_f32_32x32x16_bf16 v[0:15], v[168:171], v[176:179], v[0:15]
	s_waitcnt vmcnt(6) lgkmcnt(0)
	s_barrier
	ds_read_b128 v[164:167], v144
	ds_read_b128 v[168:171], v144 offset:4096
	ds_read_b128 v[172:175], v148
	ds_read_b128 v[176:179], v148 offset:4096
	v_mfma_f32_32x32x16_bf16 v[48:63], v[180:183], v[218:221], v[48:63]
	s_mov_b32 s64, 0x65c2280
	s_add_u32 m0, s25, 0x18000
	v_lshl_add_u64 v[226:227], v[142:143], 0, s[64:65]
	global_load_lds_dwordx4 v[226:227], off
	v_mfma_f32_32x32x16_bf16 v[32:47], v[180:183], v[222:225], v[32:47]
	v_mfma_f32_32x32x16_bf16 v[16:31], v[184:187], v[218:221], v[16:31]
	s_add_u32 m0, s25, 0x1a000
	v_lshl_add_u64 v[228:229], v[140:141], 0, s[64:65]
	global_load_lds_dwordx4 v[228:229], off
	v_mfma_f32_32x32x16_bf16 v[0:15], v[184:187], v[222:225], v[0:15]
	ds_read_b128 v[180:183], v145
	ds_read_b128 v[184:187], v145 offset:4096
	ds_read_b128 v[218:221], v149
	ds_read_b128 v[222:225], v149 offset:4096
	s_waitcnt lgkmcnt(4)
	v_mfma_f32_32x32x16_bf16 v[48:63], v[164:167], v[172:175], v[48:63]
	s_add_u32 m0, s25, 0x1c000
	v_lshl_add_u64 v[226:227], v[138:139], 0, s[64:65]
	global_load_lds_dwordx4 v[226:227], off
	v_mfma_f32_32x32x16_bf16 v[32:47], v[164:167], v[176:179], v[32:47]
	v_mfma_f32_32x32x16_bf16 v[16:31], v[168:171], v[172:175], v[16:31]
	s_add_u32 m0, s25, 0x1e000
	v_lshl_add_u64 v[228:229], v[136:137], 0, s[64:65]
	global_load_lds_dwordx4 v[228:229], off
	v_mfma_f32_32x32x16_bf16 v[0:15], v[168:171], v[176:179], v[0:15]
	ds_read_b128 v[164:167], v146
	ds_read_b128 v[168:171], v146 offset:4096
	ds_read_b128 v[172:175], v150
	ds_read_b128 v[176:179], v150 offset:4096
	s_waitcnt lgkmcnt(4)
	v_mfma_f32_32x32x16_bf16 v[48:63], v[180:183], v[218:221], v[48:63]
	s_mov_b32 s64, 0x2740280
	s_add_u32 m0, s25, 0x20000
	v_lshl_add_u64 v[226:227], v[134:135], 0, s[64:65]
	global_load_lds_dwordx4 v[226:227], off
	v_mfma_f32_32x32x16_bf16 v[32:47], v[180:183], v[222:225], v[32:47]
	v_mfma_f32_32x32x16_bf16 v[16:31], v[184:187], v[218:221], v[16:31]
	s_add_u32 m0, s25, 0x22000
	v_lshl_add_u64 v[228:229], v[132:133], 0, s[64:65]
	global_load_lds_dwordx4 v[228:229], off
	v_mfma_f32_32x32x16_bf16 v[0:15], v[184:187], v[222:225], v[0:15]
	ds_read_b128 v[180:183], v147
	ds_read_b128 v[184:187], v147 offset:4096
	ds_read_b128 v[218:221], v151
	ds_read_b128 v[222:225], v151 offset:4096
	s_waitcnt lgkmcnt(4)
	v_mfma_f32_32x32x16_bf16 v[48:63], v[164:167], v[172:175], v[48:63]
	v_mfma_f32_32x32x16_bf16 v[32:47], v[164:167], v[176:179], v[32:47]
	v_mfma_f32_32x32x16_bf16 v[16:31], v[168:171], v[172:175], v[16:31]
	v_mfma_f32_32x32x16_bf16 v[0:15], v[168:171], v[176:179], v[0:15]
	s_waitcnt vmcnt(6) lgkmcnt(0)
	s_barrier
;     ...
;   for (int kt = 0; kt < nk; ++kt) {
;     if (kt + 1 < nk) asm volatile("s_waitcnt vmcnt(6)" ::: "memory");
;     else asm volatile("s_waitcnt vmcnt(0)" ::: "memory");
;     __builtin_amdgcn_s_barrier();
;     asm volatile("" ::: "memory");
;     if (kt + 2 < nk) { const int st2 = (st >= 1) ? st - 1 : 2; GEMM_ISSUE(kt + 2, st2); }
;     const char* la = lds + st * STAGE_B;
;     const char* lb = la + 32768;
;     const unsigned sa_u = (unsigned)(size_t)la + arow_u, sb_u = (unsigned)(size_t)lb + brow_u;
;     const unsigned a0 = sa_u + co0, a1 = sa_u + co1, a2 = sa_u + co2, a3 = sa_u + co3;
;     const unsigned b0 = sb_u + co0, b1 = sb_u + co1, b2 = sb_u + co2, b3 = sb_u + co3;
;     {
;       bf16x8 p0, p1, q0, q1, u0, u1, w0, w1;
;       asm volatile(
;         "ds_read_b128 %4, %12\n\tds_read_b128 %5, %12 offset:4096\n\tds_read_b128 %6, %16\n\tds_read_b128 %7, %16 offset:4096\n\t"
;         "ds_read_b128 %8, %13\n\tds_read_b128 %9, %13 offset:4096\n\tds_read_b128 %10, %17\n\tds_read_b128 %11, %17 offset:4096\n\t"
;         "s_waitcnt lgkmcnt(4)\n\t"
;         "v_mfma_f32_32x32x16_bf16 %0, %4, %6, %0\n\tv_mfma_f32_32x32x16_bf16 %1, %4, %7, %1\n\tv_mfma_f32_32x32x16_bf16 %2, %5, %6, %2\n\tv_mfma_f32_32x32x16_bf16 %3, %5, %7, %3\n\t"
;         "ds_read_b128 %4, %14\n\tds_read_b128 %5, %14 offset:4096\n\tds_read_b128 %6, %18\n\tds_read_b128 %7, %18 offset:4096\n\t"
;         "s_waitcnt lgkmcnt(4)\n\t"
;         "v_mfma_f32_32x32x16_bf16 %0, %8, %10, %0\n\tv_mfma_f32_32x32x16_bf16 %1, %8, %11, %1\n\tv_mfma_f32_32x32x16_bf16 %2, %9, %10, %2\n\tv_mfma_f32_32x32x16_bf16 %3, %9, %11, %3\n\t"
;         "ds_read_b128 %8, %15\n\tds_read_b128 %9, %15 offset:4096\n\tds_read_b128 %10, %19\n\tds_read_b128 %11, %19 offset:4096\n\t"
;         "s_waitcnt lgkmcnt(4)\n\t"
;         "v_mfma_f32_32x32x16_bf16 %0, %4, %6, %0\n\tv_mfma_f32_32x32x16_bf16 %1, %4, %7, %1\n\tv_mfma_f32_32x32x16_bf16 %2, %5, %6, %2\n\tv_mfma_f32_32x32x16_bf16 %3, %5, %7, %3\n\t"
;         "s_waitcnt lgkmcnt(0)\n\t"
;         "v_mfma_f32_32x32x16_bf16 %0, %8, %10, %0\n\tv_mfma_f32_32x32x16_bf16 %1, %8, %11, %1\n\tv_mfma_f32_32x32x16_bf16 %2, %9, %10, %2\n\tv_mfma_f32_32x32x16_bf16 %3, %9, %11, %3"
;         : "+v"(acc[0][0]), "+v"(acc[0][1]), "+v"(acc[1][0]), "+v"(acc[1][1]),
;           "=&v"(p0), "=&v"(p1), "=&v"(q0), "=&v"(q1), "=&v"(u0), "=&v"(u1), "=&v"(w0), "=&v"(w1)
	ds_read_b128 v[164:167], v144 offset:49152
	ds_read_b128 v[168:171], v144 offset:53248
	ds_read_b128 v[172:175], v148 offset:49152
	ds_read_b128 v[176:179], v148 offset:53248
	v_mfma_f32_32x32x16_bf16 v[48:63], v[180:183], v[218:221], v[48:63]
	s_mov_b32 s64, 0x65c2300
	s_mov_b32 m0, s25
	v_lshl_add_u64 v[226:227], v[142:143], 0, s[64:65]
	global_load_lds_dwordx4 v[226:227], off
	v_mfma_f32_32x32x16_bf16 v[32:47], v[180:183], v[222:225], v[32:47]
	v_mfma_f32_32x32x16_bf16 v[16:31], v[184:187], v[218:221], v[16:31]
	s_add_u32 m0, s25, 0x2000
	v_lshl_add_u64 v[228:229], v[140:141], 0, s[64:65]
	global_load_lds_dwordx4 v[228:229], off
	v_mfma_f32_32x32x16_bf16 v[0:15], v[184:187], v[222:225], v[0:15]
	ds_read_b128 v[180:183], v145 offset:49152
	ds_read_b128 v[184:187], v145 offset:53248
	ds_read_b128 v[218:221], v149 offset:49152
	ds_read_b128 v[222:225], v149 offset:53248
	s_waitcnt lgkmcnt(4)
	v_mfma_f32_32x32x16_bf16 v[48:63], v[164:167], v[172:175], v[48:63]
	s_add_u32 m0, s25, 0x4000
	v_lshl_add_u64 v[226:227], v[138:139], 0, s[64:65]
	global_load_lds_dwordx4 v[226:227], off
	v_mfma_f32_32x32x16_bf16 v[32:47], v[164:167], v[176:179], v[32:47]
	v_mfma_f32_32x32x16_bf16 v[16:31], v[168:171], v[172:175], v[16:31]
	s_add_u32 m0, s25, 0x6000
	v_lshl_add_u64 v[228:229], v[136:137], 0, s[64:65]
	global_load_lds_dwordx4 v[228:229], off
	v_mfma_f32_32x32x16_bf16 v[0:15], v[168:171], v[176:179], v[0:15]
	ds_read_b128 v[164:167], v146 offset:49152
	ds_read_b128 v[168:171], v146 offset:53248
	ds_read_b128 v[172:175], v150 offset:49152
	ds_read_b128 v[176:179], v150 offset:53248
	s_waitcnt lgkmcnt(4)
	v_mfma_f32_32x32x16_bf16 v[48:63], v[180:183], v[218:221], v[48:63]
	s_mov_b32 s64, 0x2740300
	s_add_u32 m0, s25, 0x8000
	v_lshl_add_u64 v[226:227], v[134:135], 0, s[64:65]
	global_load_lds_dwordx4 v[226:227], off
	v_mfma_f32_32x32x16_bf16 v[32:47], v[180:183], v[222:225], v[32:47]
	v_mfma_f32_32x32x16_bf16 v[16:31], v[184:187], v[218:221], v[16:31]
	s_add_u32 m0, s25, 0xa000
	v_lshl_add_u64 v[228:229], v[132:133], 0, s[64:65]
	global_load_lds_dwordx4 v[228:229], off
	v_mfma_f32_32x32x16_bf16 v[0:15], v[184:187], v[222:225], v[0:15]
	ds_read_b128 v[180:183], v147 offset:49152
	ds_read_b128 v[184:187], v147 offset:53248
	ds_read_b128 v[218:221], v151 offset:49152
	ds_read_b128 v[222:225], v151 offset:53248
	s_waitcnt lgkmcnt(4)
	v_mfma_f32_32x32x16_bf16 v[48:63], v[164:167], v[172:175], v[48:63]
	v_mfma_f32_32x32x16_bf16 v[32:47], v[164:167], v[176:179], v[32:47]
	v_mfma_f32_32x32x16_bf16 v[16:31], v[168:171], v[172:175], v[16:31]
	v_mfma_f32_32x32x16_bf16 v[0:15], v[168:171], v[176:179], v[0:15]
	s_waitcnt vmcnt(6) lgkmcnt(0)
	s_barrier
	ds_read_b128 v[164:167], v152
	ds_read_b128 v[168:171], v152 offset:4096
	ds_read_b128 v[172:175], v157
	ds_read_b128 v[176:179], v157 offset:4096
	v_mfma_f32_32x32x16_bf16 v[48:63], v[180:183], v[218:221], v[48:63]
	s_mov_b32 s64, 0x65c2380
	s_add_u32 m0, s25, 0xc000
	v_lshl_add_u64 v[226:227], v[142:143], 0, s[64:65]
	global_load_lds_dwordx4 v[226:227], off
	v_mfma_f32_32x32x16_bf16 v[32:47], v[180:183], v[222:225], v[32:47]
	v_mfma_f32_32x32x16_bf16 v[16:31], v[184:187], v[218:221], v[16:31]
	s_add_u32 m0, s25, 0xe000
	v_lshl_add_u64 v[228:229], v[140:141], 0, s[64:65]
	global_load_lds_dwordx4 v[228:229], off
	v_mfma_f32_32x32x16_bf16 v[0:15], v[184:187], v[222:225], v[0:15]
	ds_read_b128 v[180:183], v153
	ds_read_b128 v[184:187], v153 offset:4096
	ds_read_b128 v[218:221], v158
	ds_read_b128 v[222:225], v158 offset:4096
	s_waitcnt lgkmcnt(4)
	v_mfma_f32_32x32x16_bf16 v[48:63], v[164:167], v[172:175], v[48:63]
	s_add_u32 m0, s25, 0x10000
	v_lshl_add_u64 v[226:227], v[138:139], 0, s[64:65]
	global_load_lds_dwordx4 v[226:227], off
	v_mfma_f32_32x32x16_bf16 v[32:47], v[164:167], v[176:179], v[32:47]
	v_mfma_f32_32x32x16_bf16 v[16:31], v[168:171], v[172:175], v[16:31]
	s_add_u32 m0, s25, 0x12000
	v_lshl_add_u64 v[228:229], v[136:137], 0, s[64:65]
	global_load_lds_dwordx4 v[228:229], off
	v_mfma_f32_32x32x16_bf16 v[0:15], v[168:171], v[176:179], v[0:15]
	ds_read_b128 v[164:167], v154
	ds_read_b128 v[168:171], v154 offset:4096
	ds_read_b128 v[172:175], v159
	ds_read_b128 v[176:179], v159 offset:4096
	s_waitcnt lgkmcnt(4)
	v_mfma_f32_32x32x16_bf16 v[48:63], v[180:183], v[218:221], v[48:63]
	s_mov_b32 s64, 0x2740380
	s_add_u32 m0, s25, 0x14000
	v_lshl_add_u64 v[226:227], v[134:135], 0, s[64:65]
	global_load_lds_dwordx4 v[226:227], off
	v_mfma_f32_32x32x16_bf16 v[32:47], v[180:183], v[222:225], v[32:47]
	v_mfma_f32_32x32x16_bf16 v[16:31], v[184:187], v[218:221], v[16:31]
	s_add_u32 m0, s25, 0x16000
	v_lshl_add_u64 v[228:229], v[132:133], 0, s[64:65]
	global_load_lds_dwordx4 v[228:229], off
	v_mfma_f32_32x32x16_bf16 v[0:15], v[184:187], v[222:225], v[0:15]
	ds_read_b128 v[180:183], v155
	ds_read_b128 v[184:187], v155 offset:4096
	ds_read_b128 v[218:221], v160
	ds_read_b128 v[222:225], v160 offset:4096
	s_waitcnt lgkmcnt(4)
	v_mfma_f32_32x32x16_bf16 v[48:63], v[164:167], v[172:175], v[48:63]
	v_mfma_f32_32x32x16_bf16 v[32:47], v[164:167], v[176:179], v[32:47]
	v_mfma_f32_32x32x16_bf16 v[16:31], v[168:171], v[172:175], v[16:31]
	v_mfma_f32_32x32x16_bf16 v[0:15], v[168:171], v[176:179], v[0:15]
	s_waitcnt vmcnt(6) lgkmcnt(0)
	s_barrier
;     ...
;   for (int kt = 0; kt < nk; ++kt) {
;     if (kt + 1 < nk) asm volatile("s_waitcnt vmcnt(6)" ::: "memory");
;     else asm volatile("s_waitcnt vmcnt(0)" ::: "memory");
;     __builtin_amdgcn_s_barrier();
;     asm volatile("" ::: "memory");
;     if (kt + 2 < nk) { const int st2 = (st >= 1) ? st - 1 : 2; GEMM_ISSUE(kt + 2, st2); }
;     const char* la = lds + st * STAGE_B;
;     const char* lb = la + 32768;
;     const unsigned sa_u = (unsigned)(size_t)la + arow_u, sb_u = (unsigned)(size_t)lb + brow_u;
;     const unsigned a0 = sa_u + co0, a1 = sa_u + co1, a2 = sa_u + co2, a3 = sa_u + co3;
;     const unsigned b0 = sb_u + co0, b1 = sb_u + co1, b2 = sb_u + co2, b3 = sb_u + co3;
;     {
;       bf16x8 p0, p1, q0, q1, u0, u1, w0, w1;
;       asm volatile(
;         "ds_read_b128 %4, %12\n\tds_read_b128 %5, %12 offset:4096\n\tds_read_b128 %6, %16\n\tds_read_b128 %7, %16 offset:4096\n\t"
;         "ds_read_b128 %8, %13\n\tds_read_b128 %9, %13 offset:4096\n\tds_read_b128 %10, %17\n\tds_read_b128 %11, %17 offset:4096\n\t"
;         "s_waitcnt lgkmcnt(4)\n\t"
;         "v_mfma_f32_32x32x16_bf16 %0, %4, %6, %0\n\tv_mfma_f32_32x32x16_bf16 %1, %4, %7, %1\n\tv_mfma_f32_32x32x16_bf16 %2, %5, %6, %2\n\tv_mfma_f32_32x32x16_bf16 %3, %5, %7, %3\n\t"
;         "ds_read_b128 %4, %14\n\tds_read_b128 %5, %14 offset:4096\n\tds_read_b128 %6, %18\n\tds_read_b128 %7, %18 offset:4096\n\t"
;         "s_waitcnt lgkmcnt(4)\n\t"
;         "v_mfma_f32_32x32x16_bf16 %0, %8, %10, %0\n\tv_mfma_f32_32x32x16_bf16 %1, %8, %11, %1\n\tv_mfma_f32_32x32x16_bf16 %2, %9, %10, %2\n\tv_mfma_f32_32x32x16_bf16 %3, %9, %11, %3\n\t"
;         "ds_read_b128 %8, %15\n\tds_read_b128 %9, %15 offset:4096\n\tds_read_b128 %10, %19\n\tds_read_b128 %11, %19 offset:4096\n\t"
;         "s_waitcnt lgkmcnt(4)\n\t"
;         "v_mfma_f32_32x32x16_bf16 %0, %4, %6, %0\n\tv_mfma_f32_32x32x16_bf16 %1, %4, %7, %1\n\tv_mfma_f32_32x32x16_bf16 %2, %5, %6, %2\n\tv_mfma_f32_32x32x16_bf16 %3, %5, %7, %3\n\t"
;         "s_waitcnt lgkmcnt(0)\n\t"
;         "v_mfma_f32_32x32x16_bf16 %0, %8, %10, %0\n\tv_mfma_f32_32x32x16_bf16 %1, %8, %11, %1\n\tv_mfma_f32_32x32x16_bf16 %2, %9, %10, %2\n\tv_mfma_f32_32x32x16_bf16 %3, %9, %11, %3"
;         : "+v"(acc[0][0]), "+v"(acc[0][1]), "+v"(acc[1][0]), "+v"(acc[1][1]),
;           "=&v"(p0), "=&v"(p1), "=&v"(q0), "=&v"(q1), "=&v"(u0), "=&v"(u1), "=&v"(w0), "=&v"(w1)
	ds_read_b128 v[164:167], v144
	ds_read_b128 v[168:171], v144 offset:4096
	ds_read_b128 v[172:175], v148
	ds_read_b128 v[176:179], v148 offset:4096
	v_mfma_f32_32x32x16_bf16 v[48:63], v[180:183], v[218:221], v[48:63]
	s_mov_b32 s64, 0x65c2400
	s_add_u32 m0, s25, 0x18000
	v_lshl_add_u64 v[226:227], v[142:143], 0, s[64:65]
	global_load_lds_dwordx4 v[226:227], off
	v_mfma_f32_32x32x16_bf16 v[32:47], v[180:183], v[222:225], v[32:47]
	v_mfma_f32_32x32x16_bf16 v[16:31], v[184:187], v[218:221], v[16:31]
	s_add_u32 m0, s25, 0x1a000
	v_lshl_add_u64 v[228:229], v[140:141], 0, s[64:65]
	global_load_lds_dwordx4 v[228:229], off
	v_mfma_f32_32x32x16_bf16 v[0:15], v[184:187], v[222:225], v[0:15]
	ds_read_b128 v[180:183], v145
	ds_read_b128 v[184:187], v145 offset:4096
	ds_read_b128 v[218:221], v149
	ds_read_b128 v[222:225], v149 offset:4096
	s_waitcnt lgkmcnt(4)
	v_mfma_f32_32x32x16_bf16 v[48:63], v[164:167], v[172:175], v[48:63]
	s_add_u32 m0, s25, 0x1c000
	v_lshl_add_u64 v[226:227], v[138:139], 0, s[64:65]
	global_load_lds_dwordx4 v[226:227], off
	v_mfma_f32_32x32x16_bf16 v[32:47], v[164:167], v[176:179], v[32:47]
	v_mfma_f32_32x32x16_bf16 v[16:31], v[168:171], v[172:175], v[16:31]
	s_add_u32 m0, s25, 0x1e000
	v_lshl_add_u64 v[228:229], v[136:137], 0, s[64:65]
	global_load_lds_dwordx4 v[228:229], off
	v_mfma_f32_32x32x16_bf16 v[0:15], v[168:171], v[176:179], v[0:15]
	ds_read_b128 v[164:167], v146
	ds_read_b128 v[168:171], v146 offset:4096
	ds_read_b128 v[172:175], v150
	ds_read_b128 v[176:179], v150 offset:4096
	s_waitcnt lgkmcnt(4)
	v_mfma_f32_32x32x16_bf16 v[48:63], v[180:183], v[218:221], v[48:63]
	s_mov_b32 s64, 0x2740400
	s_add_u32 m0, s25, 0x20000
	v_lshl_add_u64 v[226:227], v[134:135], 0, s[64:65]
	global_load_lds_dwordx4 v[226:227], off
	v_mfma_f32_32x32x16_bf16 v[32:47], v[180:183], v[222:225], v[32:47]
	v_mfma_f32_32x32x16_bf16 v[16:31], v[184:187], v[218:221], v[16:31]
	s_add_u32 m0, s25, 0x22000
	v_lshl_add_u64 v[228:229], v[132:133], 0, s[64:65]
	global_load_lds_dwordx4 v[228:229], off
	v_mfma_f32_32x32x16_bf16 v[0:15], v[184:187], v[222:225], v[0:15]
	ds_read_b128 v[180:183], v147
	ds_read_b128 v[184:187], v147 offset:4096
	ds_read_b128 v[218:221], v151
	ds_read_b128 v[222:225], v151 offset:4096
	s_waitcnt lgkmcnt(4)
	v_mfma_f32_32x32x16_bf16 v[48:63], v[164:167], v[172:175], v[48:63]
	v_mfma_f32_32x32x16_bf16 v[32:47], v[164:167], v[176:179], v[32:47]
	v_mfma_f32_32x32x16_bf16 v[16:31], v[168:171], v[172:175], v[16:31]
	v_mfma_f32_32x32x16_bf16 v[0:15], v[168:171], v[176:179], v[0:15]
	s_waitcnt vmcnt(6) lgkmcnt(0)
	s_barrier
	ds_read_b128 v[164:167], v144 offset:49152
	ds_read_b128 v[168:171], v144 offset:53248
	ds_read_b128 v[172:175], v148 offset:49152
	ds_read_b128 v[176:179], v148 offset:53248
	v_mfma_f32_32x32x16_bf16 v[48:63], v[180:183], v[218:221], v[48:63]
	s_mov_b32 s64, 0x65c2480
	s_mov_b32 m0, s25
	v_lshl_add_u64 v[226:227], v[142:143], 0, s[64:65]
	global_load_lds_dwordx4 v[226:227], off
	v_mfma_f32_32x32x16_bf16 v[32:47], v[180:183], v[222:225], v[32:47]
	v_mfma_f32_32x32x16_bf16 v[16:31], v[184:187], v[218:221], v[16:31]
	s_add_u32 m0, s25, 0x2000
	v_lshl_add_u64 v[228:229], v[140:141], 0, s[64:65]
	global_load_lds_dwordx4 v[228:229], off
	v_mfma_f32_32x32x16_bf16 v[0:15], v[184:187], v[222:225], v[0:15]
	ds_read_b128 v[180:183], v145 offset:49152
	ds_read_b128 v[184:187], v145 offset:53248
	ds_read_b128 v[218:221], v149 offset:49152
	ds_read_b128 v[222:225], v149 offset:53248
	s_waitcnt lgkmcnt(4)
	v_mfma_f32_32x32x16_bf16 v[48:63], v[164:167], v[172:175], v[48:63]
	s_add_u32 m0, s25, 0x4000
	v_lshl_add_u64 v[226:227], v[138:139], 0, s[64:65]
	global_load_lds_dwordx4 v[226:227], off
	v_mfma_f32_32x32x16_bf16 v[32:47], v[164:167], v[176:179], v[32:47]
	v_mfma_f32_32x32x16_bf16 v[16:31], v[168:171], v[172:175], v[16:31]
	s_add_u32 m0, s25, 0x6000
	v_lshl_add_u64 v[228:229], v[136:137], 0, s[64:65]
	global_load_lds_dwordx4 v[228:229], off
	v_mfma_f32_32x32x16_bf16 v[0:15], v[168:171], v[176:179], v[0:15]
	ds_read_b128 v[164:167], v146 offset:49152
	ds_read_b128 v[168:171], v146 offset:53248
	ds_read_b128 v[172:175], v150 offset:49152
	ds_read_b128 v[176:179], v150 offset:53248
	s_waitcnt lgkmcnt(4)
	v_mfma_f32_32x32x16_bf16 v[48:63], v[180:183], v[218:221], v[48:63]
	s_mov_b32 s64, 0x2740480
	s_add_u32 m0, s25, 0x8000
	v_lshl_add_u64 v[226:227], v[134:135], 0, s[64:65]
	global_load_lds_dwordx4 v[226:227], off
	v_mfma_f32_32x32x16_bf16 v[32:47], v[180:183], v[222:225], v[32:47]
	v_mfma_f32_32x32x16_bf16 v[16:31], v[184:187], v[218:221], v[16:31]
	s_add_u32 m0, s25, 0xa000
	v_lshl_add_u64 v[228:229], v[132:133], 0, s[64:65]
	global_load_lds_dwordx4 v[228:229], off
	v_mfma_f32_32x32x16_bf16 v[0:15], v[184:187], v[222:225], v[0:15]
	ds_read_b128 v[180:183], v147 offset:49152
	ds_read_b128 v[184:187], v147 offset:53248
	ds_read_b128 v[218:221], v151 offset:49152
	ds_read_b128 v[222:225], v151 offset:53248
	s_waitcnt lgkmcnt(4)
	v_mfma_f32_32x32x16_bf16 v[48:63], v[164:167], v[172:175], v[48:63]
	v_mfma_f32_32x32x16_bf16 v[32:47], v[164:167], v[176:179], v[32:47]
	v_mfma_f32_32x32x16_bf16 v[16:31], v[168:171], v[172:175], v[16:31]
	v_mfma_f32_32x32x16_bf16 v[0:15], v[168:171], v[176:179], v[0:15]
	s_waitcnt vmcnt(6) lgkmcnt(0)
	s_barrier
;     ...
;   for (int kt = 0; kt < nk; ++kt) {
;     if (kt + 1 < nk) asm volatile("s_waitcnt vmcnt(6)" ::: "memory");
;     else asm volatile("s_waitcnt vmcnt(0)" ::: "memory");
;     __builtin_amdgcn_s_barrier();
;     asm volatile("" ::: "memory");
;     if (kt + 2 < nk) { const int st2 = (st >= 1) ? st - 1 : 2; GEMM_ISSUE(kt + 2, st2); }
;     const char* la = lds + st * STAGE_B;
;     const char* lb = la + 32768;
;     const unsigned sa_u = (unsigned)(size_t)la + arow_u, sb_u = (unsigned)(size_t)lb + brow_u;
;     const unsigned a0 = sa_u + co0, a1 = sa_u + co1, a2 = sa_u + co2, a3 = sa_u + co3;
;     const unsigned b0 = sb_u + co0, b1 = sb_u + co1, b2 = sb_u + co2, b3 = sb_u + co3;
;     {
;       bf16x8 p0, p1, q0, q1, u0, u1, w0, w1;
;       asm volatile(
;         "ds_read_b128 %4, %12\n\tds_read_b128 %5, %12 offset:4096\n\tds_read_b128 %6, %16\n\tds_read_b128 %7, %16 offset:4096\n\t"
;         "ds_read_b128 %8, %13\n\tds_read_b128 %9, %13 offset:4096\n\tds_read_b128 %10, %17\n\tds_read_b128 %11, %17 offset:4096\n\t"
;         "s_waitcnt lgkmcnt(4)\n\t"
;         "v_mfma_f32_32x32x16_bf16 %0, %4, %6, %0\n\tv_mfma_f32_32x32x16_bf16 %1, %4, %7, %1\n\tv_mfma_f32_32x32x16_bf16 %2, %5, %6, %2\n\tv_mfma_f32_32x32x16_bf16 %3, %5, %7, %3\n\t"
;         "ds_read_b128 %4, %14\n\tds_read_b128 %5, %14 offset:4096\n\tds_read_b128 %6, %18\n\tds_read_b128 %7, %18 offset:4096\n\t"
;         "s_waitcnt lgkmcnt(4)\n\t"
;         "v_mfma_f32_32x32x16_bf16 %0, %8, %10, %0\n\tv_mfma_f32_32x32x16_bf16 %1, %8, %11, %1\n\tv_mfma_f32_32x32x16_bf16 %2, %9, %10, %2\n\tv_mfma_f32_32x32x16_bf16 %3, %9, %11, %3\n\t"
;         "ds_read_b128 %8, %15\n\tds_read_b128 %9, %15 offset:4096\n\tds_read_b128 %10, %19\n\tds_read_b128 %11, %19 offset:4096\n\t"
;         "s_waitcnt lgkmcnt(4)\n\t"
;         "v_mfma_f32_32x32x16_bf16 %0, %4, %6, %0\n\tv_mfma_f32_32x32x16_bf16 %1, %4, %7, %1\n\tv_mfma_f32_32x32x16_bf16 %2, %5, %6, %2\n\tv_mfma_f32_32x32x16_bf16 %3, %5, %7, %3\n\t"
;         "s_waitcnt lgkmcnt(0)\n\t"
;         "v_mfma_f32_32x32x16_bf16 %0, %8, %10, %0\n\tv_mfma_f32_32x32x16_bf16 %1, %8, %11, %1\n\tv_mfma_f32_32x32x16_bf16 %2, %9, %10, %2\n\tv_mfma_f32_32x32x16_bf16 %3, %9, %11, %3"
;         : "+v"(acc[0][0]), "+v"(acc[0][1]), "+v"(acc[1][0]), "+v"(acc[1][1]),
;           "=&v"(p0), "=&v"(p1), "=&v"(q0), "=&v"(q1), "=&v"(u0), "=&v"(u1), "=&v"(w0), "=&v"(w1)
	ds_read_b128 v[164:167], v152
	ds_read_b128 v[168:171], v152 offset:4096
	ds_read_b128 v[172:175], v157
	ds_read_b128 v[176:179], v157 offset:4096
	v_mfma_f32_32x32x16_bf16 v[48:63], v[180:183], v[218:221], v[48:63]
	s_mov_b32 s64, 0x65c2500
	s_add_u32 m0, s25, 0xc000
	v_lshl_add_u64 v[226:227], v[142:143], 0, s[64:65]
	global_load_lds_dwordx4 v[226:227], off
	v_mfma_f32_32x32x16_bf16 v[32:47], v[180:183], v[222:225], v[32:47]
	v_mfma_f32_32x32x16_bf16 v[16:31], v[184:187], v[218:221], v[16:31]
	s_add_u32 m0, s25, 0xe000
	v_lshl_add_u64 v[228:229], v[140:141], 0, s[64:65]
	global_load_lds_dwordx4 v[228:229], off
	v_mfma_f32_32x32x16_bf16 v[0:15], v[184:187], v[222:225], v[0:15]
	ds_read_b128 v[180:183], v153
	ds_read_b128 v[184:187], v153 offset:4096
	ds_read_b128 v[218:221], v158
	ds_read_b128 v[222:225], v158 offset:4096
	s_waitcnt lgkmcnt(4)
	v_mfma_f32_32x32x16_bf16 v[48:63], v[164:167], v[172:175], v[48:63]
	s_add_u32 m0, s25, 0x10000
	v_lshl_add_u64 v[226:227], v[138:139], 0, s[64:65]
	global_load_lds_dwordx4 v[226:227], off
	v_mfma_f32_32x32x16_bf16 v[32:47], v[164:167], v[176:179], v[32:47]
	v_mfma_f32_32x32x16_bf16 v[16:31], v[168:171], v[172:175], v[16:31]
	s_add_u32 m0, s25, 0x12000
	v_lshl_add_u64 v[228:229], v[136:137], 0, s[64:65]
	global_load_lds_dwordx4 v[228:229], off
	v_mfma_f32_32x32x16_bf16 v[0:15], v[168:171], v[176:179], v[0:15]
	ds_read_b128 v[164:167], v154
	ds_read_b128 v[168:171], v154 offset:4096
	ds_read_b128 v[172:175], v159
	ds_read_b128 v[176:179], v159 offset:4096
	s_waitcnt lgkmcnt(4)
	v_mfma_f32_32x32x16_bf16 v[48:63], v[180:183], v[218:221], v[48:63]
	s_mov_b32 s64, 0x2740500
	s_add_u32 m0, s25, 0x14000
	v_lshl_add_u64 v[226:227], v[134:135], 0, s[64:65]
	global_load_lds_dwordx4 v[226:227], off
	v_mfma_f32_32x32x16_bf16 v[32:47], v[180:183], v[222:225], v[32:47]
	v_mfma_f32_32x32x16_bf16 v[16:31], v[184:187], v[218:221], v[16:31]
	s_add_u32 m0, s25, 0x16000
	v_lshl_add_u64 v[228:229], v[132:133], 0, s[64:65]
	global_load_lds_dwordx4 v[228:229], off
	v_mfma_f32_32x32x16_bf16 v[0:15], v[184:187], v[222:225], v[0:15]
	ds_read_b128 v[180:183], v155
	ds_read_b128 v[184:187], v155 offset:4096
	ds_read_b128 v[218:221], v160
	ds_read_b128 v[222:225], v160 offset:4096
	s_waitcnt lgkmcnt(4)
	v_mfma_f32_32x32x16_bf16 v[48:63], v[164:167], v[172:175], v[48:63]
	v_mfma_f32_32x32x16_bf16 v[32:47], v[164:167], v[176:179], v[32:47]
	v_mfma_f32_32x32x16_bf16 v[16:31], v[168:171], v[172:175], v[16:31]
	v_mfma_f32_32x32x16_bf16 v[0:15], v[168:171], v[176:179], v[0:15]
	s_waitcnt vmcnt(6) lgkmcnt(0)
	s_barrier
	ds_read_b128 v[164:167], v144
	ds_read_b128 v[168:171], v144 offset:4096
	ds_read_b128 v[172:175], v148
	ds_read_b128 v[176:179], v148 offset:4096
	v_mfma_f32_32x32x16_bf16 v[48:63], v[180:183], v[218:221], v[48:63]
	s_mov_b32 s64, 0x65c2580
	s_add_u32 m0, s25, 0x18000
	v_lshl_add_u64 v[226:227], v[142:143], 0, s[64:65]
	global_load_lds_dwordx4 v[226:227], off
	v_mfma_f32_32x32x16_bf16 v[32:47], v[180:183], v[222:225], v[32:47]
	v_mfma_f32_32x32x16_bf16 v[16:31], v[184:187], v[218:221], v[16:31]
	s_add_u32 m0, s25, 0x1a000
	v_lshl_add_u64 v[228:229], v[140:141], 0, s[64:65]
	global_load_lds_dwordx4 v[228:229], off
	v_mfma_f32_32x32x16_bf16 v[0:15], v[184:187], v[222:225], v[0:15]
	ds_read_b128 v[180:183], v145
	ds_read_b128 v[184:187], v145 offset:4096
	ds_read_b128 v[218:221], v149
	ds_read_b128 v[222:225], v149 offset:4096
	s_waitcnt lgkmcnt(4)
	v_mfma_f32_32x32x16_bf16 v[48:63], v[164:167], v[172:175], v[48:63]
	s_add_u32 m0, s25, 0x1c000
	v_lshl_add_u64 v[226:227], v[138:139], 0, s[64:65]
	global_load_lds_dwordx4 v[226:227], off
	v_mfma_f32_32x32x16_bf16 v[32:47], v[164:167], v[176:179], v[32:47]
	v_mfma_f32_32x32x16_bf16 v[16:31], v[168:171], v[172:175], v[16:31]
	s_add_u32 m0, s25, 0x1e000
	v_lshl_add_u64 v[228:229], v[136:137], 0, s[64:65]
	global_load_lds_dwordx4 v[228:229], off
	v_mfma_f32_32x32x16_bf16 v[0:15], v[168:171], v[176:179], v[0:15]
	ds_read_b128 v[164:167], v146
	ds_read_b128 v[168:171], v146 offset:4096
	ds_read_b128 v[172:175], v150
	ds_read_b128 v[176:179], v150 offset:4096
	s_waitcnt lgkmcnt(4)
	v_mfma_f32_32x32x16_bf16 v[48:63], v[180:183], v[218:221], v[48:63]
	s_mov_b32 s64, 0x2740580
	s_add_u32 m0, s25, 0x20000
	v_lshl_add_u64 v[226:227], v[134:135], 0, s[64:65]
	global_load_lds_dwordx4 v[226:227], off
	v_mfma_f32_32x32x16_bf16 v[32:47], v[180:183], v[222:225], v[32:47]
	v_mfma_f32_32x32x16_bf16 v[16:31], v[184:187], v[218:221], v[16:31]
	s_add_u32 m0, s25, 0x22000
	v_lshl_add_u64 v[228:229], v[132:133], 0, s[64:65]
	global_load_lds_dwordx4 v[228:229], off
	v_mfma_f32_32x32x16_bf16 v[0:15], v[184:187], v[222:225], v[0:15]
	ds_read_b128 v[180:183], v147
	ds_read_b128 v[184:187], v147 offset:4096
	ds_read_b128 v[218:221], v151
	ds_read_b128 v[222:225], v151 offset:4096
	s_waitcnt lgkmcnt(4)
	v_mfma_f32_32x32x16_bf16 v[48:63], v[164:167], v[172:175], v[48:63]
	v_mfma_f32_32x32x16_bf16 v[32:47], v[164:167], v[176:179], v[32:47]
	v_mfma_f32_32x32x16_bf16 v[16:31], v[168:171], v[172:175], v[16:31]
	v_mfma_f32_32x32x16_bf16 v[0:15], v[168:171], v[176:179], v[0:15]
	s_waitcnt vmcnt(6) lgkmcnt(0)
	s_barrier
;     ...
;   for (int kt = 0; kt < nk; ++kt) {
;     if (kt + 1 < nk) asm volatile("s_waitcnt vmcnt(6)" ::: "memory");
;     else asm volatile("s_waitcnt vmcnt(0)" ::: "memory");
;     __builtin_amdgcn_s_barrier();
;     asm volatile("" ::: "memory");
;     if (kt + 2 < nk) { const int st2 = (st >= 1) ? st - 1 : 2; GEMM_ISSUE(kt + 2, st2); }
;     const char* la = lds + st * STAGE_B;
;     const char* lb = la + 32768;
;     const unsigned sa_u = (unsigned)(size_t)la + arow_u, sb_u = (unsigned)(size_t)lb + brow_u;
;     const unsigned a0 = sa_u + co0, a1 = sa_u + co1, a2 = sa_u + co2, a3 = sa_u + co3;
;     const unsigned b0 = sb_u + co0, b1 = sb_u + co1, b2 = sb_u + co2, b3 = sb_u + co3;
;     {
;       bf16x8 p0, p1, q0, q1, u0, u1, w0, w1;
;       asm volatile(
;         "ds_read_b128 %4, %12\n\tds_read_b128 %5, %12 offset:4096\n\tds_read_b128 %6, %16\n\tds_read_b128 %7, %16 offset:4096\n\t"
;         "ds_read_b128 %8, %13\n\tds_read_b128 %9, %13 offset:4096\n\tds_read_b128 %10, %17\n\tds_read_b128 %11, %17 offset:4096\n\t"
;         "s_waitcnt lgkmcnt(4)\n\t"
;         "v_mfma_f32_32x32x16_bf16 %0, %4, %6, %0\n\tv_mfma_f32_32x32x16_bf16 %1, %4, %7, %1\n\tv_mfma_f32_32x32x16_bf16 %2, %5, %6, %2\n\tv_mfma_f32_32x32x16_bf16 %3, %5, %7, %3\n\t"
;         "ds_read_b128 %4, %14\n\tds_read_b128 %5, %14 offset:4096\n\tds_read_b128 %6, %18\n\tds_read_b128 %7, %18 offset:4096\n\t"
;         "s_waitcnt lgkmcnt(4)\n\t"
;         "v_mfma_f32_32x32x16_bf16 %0, %8, %10, %0\n\tv_mfma_f32_32x32x16_bf16 %1, %8, %11, %1\n\tv_mfma_f32_32x32x16_bf16 %2, %9, %10, %2\n\tv_mfma_f32_32x32x16_bf16 %3, %9, %11, %3\n\t"
;         "ds_read_b128 %8, %15\n\tds_read_b128 %9, %15 offset:4096\n\tds_read_b128 %10, %19\n\tds_read_b128 %11, %19 offset:4096\n\t"
;         "s_waitcnt lgkmcnt(4)\n\t"
;         "v_mfma_f32_32x32x16_bf16 %0, %4, %6, %0\n\tv_mfma_f32_32x32x16_bf16 %1, %4, %7, %1\n\tv_mfma_f32_32x32x16_bf16 %2, %5, %6, %2\n\tv_mfma_f32_32x32x16_bf16 %3, %5, %7, %3\n\t"
;         "s_waitcnt lgkmcnt(0)\n\t"
;         "v_mfma_f32_32x32x16_bf16 %0, %8, %10, %0\n\tv_mfma_f32_32x32x16_bf16 %1, %8, %11, %1\n\tv_mfma_f32_32x32x16_bf16 %2, %9, %10, %2\n\tv_mfma_f32_32x32x16_bf16 %3, %9, %11, %3"
;         : "+v"(acc[0][0]), "+v"(acc[0][1]), "+v"(acc[1][0]), "+v"(acc[1][1]),
;           "=&v"(p0), "=&v"(p1), "=&v"(q0), "=&v"(q1), "=&v"(u0), "=&v"(u1), "=&v"(w0), "=&v"(w1)
	ds_read_b128 v[164:167], v144 offset:49152
	ds_read_b128 v[168:171], v144 offset:53248
	ds_read_b128 v[172:175], v148 offset:49152
	ds_read_b128 v[176:179], v148 offset:53248
	v_mfma_f32_32x32x16_bf16 v[48:63], v[180:183], v[218:221], v[48:63]
	s_mov_b32 s64, 0x65c2600
	s_mov_b32 m0, s25
	v_lshl_add_u64 v[226:227], v[142:143], 0, s[64:65]
	global_load_lds_dwordx4 v[226:227], off
	v_mfma_f32_32x32x16_bf16 v[32:47], v[180:183], v[222:225], v[32:47]
	v_mfma_f32_32x32x16_bf16 v[16:31], v[184:187], v[218:221], v[16:31]
	s_add_u32 m0, s25, 0x2000
	v_lshl_add_u64 v[228:229], v[140:141], 0, s[64:65]
	global_load_lds_dwordx4 v[228:229], off
	v_mfma_f32_32x32x16_bf16 v[0:15], v[184:187], v[222:225], v[0:15]
	ds_read_b128 v[180:183], v145 offset:49152
	ds_read_b128 v[184:187], v145 offset:53248
	ds_read_b128 v[218:221], v149 offset:49152
	ds_read_b128 v[222:225], v149 offset:53248
	s_waitcnt lgkmcnt(4)
	v_mfma_f32_32x32x16_bf16 v[48:63], v[164:167], v[172:175], v[48:63]
	s_add_u32 m0, s25, 0x4000
	v_lshl_add_u64 v[226:227], v[138:139], 0, s[64:65]
	global_load_lds_dwordx4 v[226:227], off
	v_mfma_f32_32x32x16_bf16 v[32:47], v[164:167], v[176:179], v[32:47]
	v_mfma_f32_32x32x16_bf16 v[16:31], v[168:171], v[172:175], v[16:31]
	s_add_u32 m0, s25, 0x6000
	v_lshl_add_u64 v[228:229], v[136:137], 0, s[64:65]
	global_load_lds_dwordx4 v[228:229], off
	v_mfma_f32_32x32x16_bf16 v[0:15], v[168:171], v[176:179], v[0:15]
	ds_read_b128 v[164:167], v146 offset:49152
	ds_read_b128 v[168:171], v146 offset:53248
	ds_read_b128 v[172:175], v150 offset:49152
	ds_read_b128 v[176:179], v150 offset:53248
	s_waitcnt lgkmcnt(4)
	v_mfma_f32_32x32x16_bf16 v[48:63], v[180:183], v[218:221], v[48:63]
	s_mov_b32 s64, 0x2740600
	s_add_u32 m0, s25, 0x8000
	v_lshl_add_u64 v[226:227], v[134:135], 0, s[64:65]
	global_load_lds_dwordx4 v[226:227], off
	v_mfma_f32_32x32x16_bf16 v[32:47], v[180:183], v[222:225], v[32:47]
	v_mfma_f32_32x32x16_bf16 v[16:31], v[184:187], v[218:221], v[16:31]
	s_add_u32 m0, s25, 0xa000
	v_lshl_add_u64 v[228:229], v[132:133], 0, s[64:65]
	global_load_lds_dwordx4 v[228:229], off
	v_mfma_f32_32x32x16_bf16 v[0:15], v[184:187], v[222:225], v[0:15]
	ds_read_b128 v[180:183], v147 offset:49152
	ds_read_b128 v[184:187], v147 offset:53248
	ds_read_b128 v[218:221], v151 offset:49152
	ds_read_b128 v[222:225], v151 offset:53248
	s_waitcnt lgkmcnt(4)
	v_mfma_f32_32x32x16_bf16 v[48:63], v[164:167], v[172:175], v[48:63]
	v_mfma_f32_32x32x16_bf16 v[32:47], v[164:167], v[176:179], v[32:47]
	v_mfma_f32_32x32x16_bf16 v[16:31], v[168:171], v[172:175], v[16:31]
	v_mfma_f32_32x32x16_bf16 v[0:15], v[168:171], v[176:179], v[0:15]
	s_waitcnt vmcnt(6) lgkmcnt(0)
	s_barrier
	ds_read_b128 v[164:167], v152
	ds_read_b128 v[168:171], v152 offset:4096
	ds_read_b128 v[172:175], v157
	ds_read_b128 v[176:179], v157 offset:4096
	v_mfma_f32_32x32x16_bf16 v[48:63], v[180:183], v[218:221], v[48:63]
	s_mov_b32 s64, 0x65c2680
	s_add_u32 m0, s25, 0xc000
	v_lshl_add_u64 v[226:227], v[142:143], 0, s[64:65]
	global_load_lds_dwordx4 v[226:227], off
	v_mfma_f32_32x32x16_bf16 v[32:47], v[180:183], v[222:225], v[32:47]
	v_mfma_f32_32x32x16_bf16 v[16:31], v[184:187], v[218:221], v[16:31]
	s_add_u32 m0, s25, 0xe000
	v_lshl_add_u64 v[228:229], v[140:141], 0, s[64:65]
	global_load_lds_dwordx4 v[228:229], off
	v_mfma_f32_32x32x16_bf16 v[0:15], v[184:187], v[222:225], v[0:15]
	ds_read_b128 v[180:183], v153
	ds_read_b128 v[184:187], v153 offset:4096
	ds_read_b128 v[218:221], v158
	ds_read_b128 v[222:225], v158 offset:4096
	s_waitcnt lgkmcnt(4)
	v_mfma_f32_32x32x16_bf16 v[48:63], v[164:167], v[172:175], v[48:63]
	s_add_u32 m0, s25, 0x10000
	v_lshl_add_u64 v[226:227], v[138:139], 0, s[64:65]
	global_load_lds_dwordx4 v[226:227], off
	v_mfma_f32_32x32x16_bf16 v[32:47], v[164:167], v[176:179], v[32:47]
	v_mfma_f32_32x32x16_bf16 v[16:31], v[168:171], v[172:175], v[16:31]
	s_add_u32 m0, s25, 0x12000
	v_lshl_add_u64 v[228:229], v[136:137], 0, s[64:65]
	global_load_lds_dwordx4 v[228:229], off
	v_mfma_f32_32x32x16_bf16 v[0:15], v[168:171], v[176:179], v[0:15]
	ds_read_b128 v[164:167], v154
	ds_read_b128 v[168:171], v154 offset:4096
	ds_read_b128 v[172:175], v159
	ds_read_b128 v[176:179], v159 offset:4096
	s_waitcnt lgkmcnt(4)
	v_mfma_f32_32x32x16_bf16 v[48:63], v[180:183], v[218:221], v[48:63]
	s_mov_b32 s64, 0x2740680
	s_add_u32 m0, s25, 0x14000
	v_lshl_add_u64 v[226:227], v[134:135], 0, s[64:65]
	global_load_lds_dwordx4 v[226:227], off
	v_mfma_f32_32x32x16_bf16 v[32:47], v[180:183], v[222:225], v[32:47]
	v_mfma_f32_32x32x16_bf16 v[16:31], v[184:187], v[218:221], v[16:31]
	s_add_u32 m0, s25, 0x16000
	v_lshl_add_u64 v[228:229], v[132:133], 0, s[64:65]
	global_load_lds_dwordx4 v[228:229], off
	v_mfma_f32_32x32x16_bf16 v[0:15], v[184:187], v[222:225], v[0:15]
	ds_read_b128 v[180:183], v155
	ds_read_b128 v[184:187], v155 offset:4096
	ds_read_b128 v[218:221], v160
	ds_read_b128 v[222:225], v160 offset:4096
	s_waitcnt lgkmcnt(4)
	v_mfma_f32_32x32x16_bf16 v[48:63], v[164:167], v[172:175], v[48:63]
	v_mfma_f32_32x32x16_bf16 v[32:47], v[164:167], v[176:179], v[32:47]
	v_mfma_f32_32x32x16_bf16 v[16:31], v[168:171], v[172:175], v[16:31]
	v_mfma_f32_32x32x16_bf16 v[0:15], v[168:171], v[176:179], v[0:15]
	s_waitcnt vmcnt(6) lgkmcnt(0)
	s_barrier
;     ...
;   for (int kt = 0; kt < nk; ++kt) {
;     if (kt + 1 < nk) asm volatile("s_waitcnt vmcnt(6)" ::: "memory");
;     else asm volatile("s_waitcnt vmcnt(0)" ::: "memory");
;     __builtin_amdgcn_s_barrier();
;     asm volatile("" ::: "memory");
;     if (kt + 2 < nk) { const int st2 = (st >= 1) ? st - 1 : 2; GEMM_ISSUE(kt + 2, st2); }
;     const char* la = lds + st * STAGE_B;
;     const char* lb = la + 32768;
;     const unsigned sa_u = (unsigned)(size_t)la + arow_u, sb_u = (unsigned)(size_t)lb + brow_u;
;     const unsigned a0 = sa_u + co0, a1 = sa_u + co1, a2 = sa_u + co2, a3 = sa_u + co3;
;     const unsigned b0 = sb_u + co0, b1 = sb_u + co1, b2 = sb_u + co2, b3 = sb_u + co3;
;     {
;       bf16x8 p0, p1, q0, q1, u0, u1, w0, w1;
;       asm volatile(
;         "ds_read_b128 %4, %12\n\tds_read_b128 %5, %12 offset:4096\n\tds_read_b128 %6, %16\n\tds_read_b128 %7, %16 offset:4096\n\t"
;         "ds_read_b128 %8, %13\n\tds_read_b128 %9, %13 offset:4096\n\tds_read_b128 %10, %17\n\tds_read_b128 %11, %17 offset:4096\n\t"
;         "s_waitcnt lgkmcnt(4)\n\t"
;         "v_mfma_f32_32x32x16_bf16 %0, %4, %6, %0\n\tv_mfma_f32_32x32x16_bf16 %1, %4, %7, %1\n\tv_mfma_f32_32x32x16_bf16 %2, %5, %6, %2\n\tv_mfma_f32_32x32x16_bf16 %3, %5, %7, %3\n\t"
;         "ds_read_b128 %4, %14\n\tds_read_b128 %5, %14 offset:4096\n\tds_read_b128 %6, %18\n\tds_read_b128 %7, %18 offset:4096\n\t"
;         "s_waitcnt lgkmcnt(4)\n\t"
;         "v_mfma_f32_32x32x16_bf16 %0, %8, %10, %0\n\tv_mfma_f32_32x32x16_bf16 %1, %8, %11, %1\n\tv_mfma_f32_32x32x16_bf16 %2, %9, %10, %2\n\tv_mfma_f32_32x32x16_bf16 %3, %9, %11, %3\n\t"
;         "ds_read_b128 %8, %15\n\tds_read_b128 %9, %15 offset:4096\n\tds_read_b128 %10, %19\n\tds_read_b128 %11, %19 offset:4096\n\t"
;         "s_waitcnt lgkmcnt(4)\n\t"
;         "v_mfma_f32_32x32x16_bf16 %0, %4, %6, %0\n\tv_mfma_f32_32x32x16_bf16 %1, %4, %7, %1\n\tv_mfma_f32_32x32x16_bf16 %2, %5, %6, %2\n\tv_mfma_f32_32x32x16_bf16 %3, %5, %7, %3\n\t"
;         "s_waitcnt lgkmcnt(0)\n\t"
;         "v_mfma_f32_32x32x16_bf16 %0, %8, %10, %0\n\tv_mfma_f32_32x32x16_bf16 %1, %8, %11, %1\n\tv_mfma_f32_32x32x16_bf16 %2, %9, %10, %2\n\tv_mfma_f32_32x32x16_bf16 %3, %9, %11, %3"
;         : "+v"(acc[0][0]), "+v"(acc[0][1]), "+v"(acc[1][0]), "+v"(acc[1][1]),
;           "=&v"(p0), "=&v"(p1), "=&v"(q0), "=&v"(q1), "=&v"(u0), "=&v"(u1), "=&v"(w0), "=&v"(w1)
	ds_read_b128 v[164:167], v144
	ds_read_b128 v[168:171], v144 offset:4096
	ds_read_b128 v[172:175], v148
	ds_read_b128 v[176:179], v148 offset:4096
	v_mfma_f32_32x32x16_bf16 v[48:63], v[180:183], v[218:221], v[48:63]
	s_mov_b32 s64, 0x65c2700
	s_add_u32 m0, s25, 0x18000
	v_lshl_add_u64 v[226:227], v[142:143], 0, s[64:65]
	global_load_lds_dwordx4 v[226:227], off
	v_mfma_f32_32x32x16_bf16 v[32:47], v[180:183], v[222:225], v[32:47]
	v_mfma_f32_32x32x16_bf16 v[16:31], v[184:187], v[218:221], v[16:31]
	s_add_u32 m0, s25, 0x1a000
	v_lshl_add_u64 v[228:229], v[140:141], 0, s[64:65]
	global_load_lds_dwordx4 v[228:229], off
	v_mfma_f32_32x32x16_bf16 v[0:15], v[184:187], v[222:225], v[0:15]
	ds_read_b128 v[180:183], v145
	ds_read_b128 v[184:187], v145 offset:4096
	ds_read_b128 v[218:221], v149
	ds_read_b128 v[222:225], v149 offset:4096
	s_waitcnt lgkmcnt(4)
	v_mfma_f32_32x32x16_bf16 v[48:63], v[164:167], v[172:175], v[48:63]
	s_add_u32 m0, s25, 0x1c000
	v_lshl_add_u64 v[226:227], v[138:139], 0, s[64:65]
	global_load_lds_dwordx4 v[226:227], off
	v_mfma_f32_32x32x16_bf16 v[32:47], v[164:167], v[176:179], v[32:47]
	v_mfma_f32_32x32x16_bf16 v[16:31], v[168:171], v[172:175], v[16:31]
	s_add_u32 m0, s25, 0x1e000
	v_lshl_add_u64 v[228:229], v[136:137], 0, s[64:65]
	global_load_lds_dwordx4 v[228:229], off
	v_mfma_f32_32x32x16_bf16 v[0:15], v[168:171], v[176:179], v[0:15]
	ds_read_b128 v[164:167], v146
	ds_read_b128 v[168:171], v146 offset:4096
	ds_read_b128 v[172:175], v150
	ds_read_b128 v[176:179], v150 offset:4096
	s_waitcnt lgkmcnt(4)
	v_mfma_f32_32x32x16_bf16 v[48:63], v[180:183], v[218:221], v[48:63]
	s_mov_b32 s64, 0x2740700
	s_add_u32 m0, s25, 0x20000
	v_lshl_add_u64 v[226:227], v[134:135], 0, s[64:65]
	global_load_lds_dwordx4 v[226:227], off
	v_mfma_f32_32x32x16_bf16 v[32:47], v[180:183], v[222:225], v[32:47]
	v_mfma_f32_32x32x16_bf16 v[16:31], v[184:187], v[218:221], v[16:31]
	s_add_u32 m0, s25, 0x22000
	v_lshl_add_u64 v[228:229], v[132:133], 0, s[64:65]
	global_load_lds_dwordx4 v[228:229], off
	v_mfma_f32_32x32x16_bf16 v[0:15], v[184:187], v[222:225], v[0:15]
	ds_read_b128 v[180:183], v147
	ds_read_b128 v[184:187], v147 offset:4096
	ds_read_b128 v[218:221], v151
	ds_read_b128 v[222:225], v151 offset:4096
	s_waitcnt lgkmcnt(4)
	v_mfma_f32_32x32x16_bf16 v[48:63], v[164:167], v[172:175], v[48:63]
	v_mfma_f32_32x32x16_bf16 v[32:47], v[164:167], v[176:179], v[32:47]
	v_mfma_f32_32x32x16_bf16 v[16:31], v[168:171], v[172:175], v[16:31]
	v_mfma_f32_32x32x16_bf16 v[0:15], v[168:171], v[176:179], v[0:15]
	s_waitcnt vmcnt(6) lgkmcnt(0)
	s_barrier
	ds_read_b128 v[164:167], v144 offset:49152
	ds_read_b128 v[168:171], v144 offset:53248
	ds_read_b128 v[172:175], v148 offset:49152
	ds_read_b128 v[176:179], v148 offset:53248
	v_mfma_f32_32x32x16_bf16 v[48:63], v[180:183], v[218:221], v[48:63]
	s_mov_b32 s64, 0x65c2780
	s_mov_b32 m0, s25
	v_lshl_add_u64 v[226:227], v[142:143], 0, s[64:65]
	global_load_lds_dwordx4 v[226:227], off
	v_mfma_f32_32x32x16_bf16 v[32:47], v[180:183], v[222:225], v[32:47]
	v_mfma_f32_32x32x16_bf16 v[16:31], v[184:187], v[218:221], v[16:31]
	s_add_u32 m0, s25, 0x2000
	v_lshl_add_u64 v[228:229], v[140:141], 0, s[64:65]
	global_load_lds_dwordx4 v[228:229], off
	v_mfma_f32_32x32x16_bf16 v[0:15], v[184:187], v[222:225], v[0:15]
	ds_read_b128 v[180:183], v145 offset:49152
	ds_read_b128 v[184:187], v145 offset:53248
	ds_read_b128 v[218:221], v149 offset:49152
	ds_read_b128 v[222:225], v149 offset:53248
	s_waitcnt lgkmcnt(4)
	v_mfma_f32_32x32x16_bf16 v[48:63], v[164:167], v[172:175], v[48:63]
	s_add_u32 m0, s25, 0x4000
	v_lshl_add_u64 v[226:227], v[138:139], 0, s[64:65]
	global_load_lds_dwordx4 v[226:227], off
	v_mfma_f32_32x32x16_bf16 v[32:47], v[164:167], v[176:179], v[32:47]
	v_mfma_f32_32x32x16_bf16 v[16:31], v[168:171], v[172:175], v[16:31]
	s_add_u32 m0, s25, 0x6000
	v_lshl_add_u64 v[228:229], v[136:137], 0, s[64:65]
	global_load_lds_dwordx4 v[228:229], off
	v_mfma_f32_32x32x16_bf16 v[0:15], v[168:171], v[176:179], v[0:15]
	ds_read_b128 v[164:167], v146 offset:49152
	ds_read_b128 v[168:171], v146 offset:53248
	ds_read_b128 v[172:175], v150 offset:49152
	ds_read_b128 v[176:179], v150 offset:53248
	s_waitcnt lgkmcnt(4)
	v_mfma_f32_32x32x16_bf16 v[48:63], v[180:183], v[218:221], v[48:63]
	s_mov_b32 s64, 0x2740780
	s_add_u32 m0, s25, 0x8000
	v_lshl_add_u64 v[226:227], v[134:135], 0, s[64:65]
	global_load_lds_dwordx4 v[226:227], off
	v_mfma_f32_32x32x16_bf16 v[32:47], v[180:183], v[222:225], v[32:47]
	v_mfma_f32_32x32x16_bf16 v[16:31], v[184:187], v[218:221], v[16:31]
	s_add_u32 m0, s25, 0xa000
	v_lshl_add_u64 v[228:229], v[132:133], 0, s[64:65]
	global_load_lds_dwordx4 v[228:229], off
	v_mfma_f32_32x32x16_bf16 v[0:15], v[184:187], v[222:225], v[0:15]
	ds_read_b128 v[180:183], v147 offset:49152
	ds_read_b128 v[184:187], v147 offset:53248
	ds_read_b128 v[218:221], v151 offset:49152
	ds_read_b128 v[222:225], v151 offset:53248
	s_waitcnt lgkmcnt(4)
	v_mfma_f32_32x32x16_bf16 v[48:63], v[164:167], v[172:175], v[48:63]
	v_mfma_f32_32x32x16_bf16 v[32:47], v[164:167], v[176:179], v[32:47]
	v_mfma_f32_32x32x16_bf16 v[16:31], v[168:171], v[172:175], v[16:31]
	v_mfma_f32_32x32x16_bf16 v[0:15], v[168:171], v[176:179], v[0:15]
	s_waitcnt vmcnt(6) lgkmcnt(0)
	s_barrier
;     ...
;   for (int kt = 0; kt < nk; ++kt) {
;     if (kt + 1 < nk) asm volatile("s_waitcnt vmcnt(6)" ::: "memory");
;     else asm volatile("s_waitcnt vmcnt(0)" ::: "memory");
;     __builtin_amdgcn_s_barrier();
;     asm volatile("" ::: "memory");
;     if (kt + 2 < nk) { const int st2 = (st >= 1) ? st - 1 : 2; GEMM_ISSUE(kt + 2, st2); }
;     const char* la = lds + st * STAGE_B;
;     const char* lb = la + 32768;
;     const unsigned sa_u = (unsigned)(size_t)la + arow_u, sb_u = (unsigned)(size_t)lb + brow_u;
;     const unsigned a0 = sa_u + co0, a1 = sa_u + co1, a2 = sa_u + co2, a3 = sa_u + co3;
;     const unsigned b0 = sb_u + co0, b1 = sb_u + co1, b2 = sb_u + co2, b3 = sb_u + co3;
;     {
;       bf16x8 p0, p1, q0, q1, u0, u1, w0, w1;
;       asm volatile(
;         "ds_read_b128 %4, %12\n\tds_read_b128 %5, %12 offset:4096\n\tds_read_b128 %6, %16\n\tds_read_b128 %7, %16 offset:4096\n\t"
;         "ds_read_b128 %8, %13\n\tds_read_b128 %9, %13 offset:4096\n\tds_read_b128 %10, %17\n\tds_read_b128 %11, %17 offset:4096\n\t"
;         "s_waitcnt lgkmcnt(4)\n\t"
;         "v_mfma_f32_32x32x16_bf16 %0, %4, %6, %0\n\tv_mfma_f32_32x32x16_bf16 %1, %4, %7, %1\n\tv_mfma_f32_32x32x16_bf16 %2, %5, %6, %2\n\tv_mfma_f32_32x32x16_bf16 %3, %5, %7, %3\n\t"
;         "ds_read_b128 %4, %14\n\tds_read_b128 %5, %14 offset:4096\n\tds_read_b128 %6, %18\n\tds_read_b128 %7, %18 offset:4096\n\t"
;         "s_waitcnt lgkmcnt(4)\n\t"
;         "v_mfma_f32_32x32x16_bf16 %0, %8, %10, %0\n\tv_mfma_f32_32x32x16_bf16 %1, %8, %11, %1\n\tv_mfma_f32_32x32x16_bf16 %2, %9, %10, %2\n\tv_mfma_f32_32x32x16_bf16 %3, %9, %11, %3\n\t"
;         "ds_read_b128 %8, %15\n\tds_read_b128 %9, %15 offset:4096\n\tds_read_b128 %10, %19\n\tds_read_b128 %11, %19 offset:4096\n\t"
;         "s_waitcnt lgkmcnt(4)\n\t"
;         "v_mfma_f32_32x32x16_bf16 %0, %4, %6, %0\n\tv_mfma_f32_32x32x16_bf16 %1, %4, %7, %1\n\tv_mfma_f32_32x32x16_bf16 %2, %5, %6, %2\n\tv_mfma_f32_32x32x16_bf16 %3, %5, %7, %3\n\t"
;         "s_waitcnt lgkmcnt(0)\n\t"
;         "v_mfma_f32_32x32x16_bf16 %0, %8, %10, %0\n\tv_mfma_f32_32x32x16_bf16 %1, %8, %11, %1\n\tv_mfma_f32_32x32x16_bf16 %2, %9, %10, %2\n\tv_mfma_f32_32x32x16_bf16 %3, %9, %11, %3"
;         : "+v"(acc[0][0]), "+v"(acc[0][1]), "+v"(acc[1][0]), "+v"(acc[1][1]),
;           "=&v"(p0), "=&v"(p1), "=&v"(q0), "=&v"(q1), "=&v"(u0), "=&v"(u1), "=&v"(w0), "=&v"(w1)
	ds_read_b128 v[164:167], v152
	ds_read_b128 v[168:171], v152 offset:4096
	ds_read_b128 v[172:175], v157
	ds_read_b128 v[176:179], v157 offset:4096
	v_mfma_f32_32x32x16_bf16 v[48:63], v[180:183], v[218:221], v[48:63]
	v_mfma_f32_32x32x16_bf16 v[32:47], v[180:183], v[222:225], v[32:47]
	v_mfma_f32_32x32x16_bf16 v[16:31], v[184:187], v[218:221], v[16:31]
	v_mfma_f32_32x32x16_bf16 v[0:15], v[184:187], v[222:225], v[0:15]
	ds_read_b128 v[180:183], v153
	ds_read_b128 v[184:187], v153 offset:4096
	ds_read_b128 v[218:221], v158
	ds_read_b128 v[222:225], v158 offset:4096
	s_waitcnt lgkmcnt(4)
	v_mfma_f32_32x32x16_bf16 v[48:63], v[164:167], v[172:175], v[48:63]
	v_mfma_f32_32x32x16_bf16 v[32:47], v[164:167], v[176:179], v[32:47]
	v_mfma_f32_32x32x16_bf16 v[16:31], v[168:171], v[172:175], v[16:31]
	v_mfma_f32_32x32x16_bf16 v[0:15], v[168:171], v[176:179], v[0:15]
	ds_read_b128 v[164:167], v154
	ds_read_b128 v[168:171], v154 offset:4096
	ds_read_b128 v[172:175], v159
	ds_read_b128 v[176:179], v159 offset:4096
	s_waitcnt lgkmcnt(4)
	v_mfma_f32_32x32x16_bf16 v[48:63], v[180:183], v[218:221], v[48:63]
	v_mfma_f32_32x32x16_bf16 v[32:47], v[180:183], v[222:225], v[32:47]
	v_mfma_f32_32x32x16_bf16 v[16:31], v[184:187], v[218:221], v[16:31]
	v_mfma_f32_32x32x16_bf16 v[0:15], v[184:187], v[222:225], v[0:15]
	ds_read_b128 v[180:183], v155
	ds_read_b128 v[184:187], v155 offset:4096
	ds_read_b128 v[218:221], v160
	ds_read_b128 v[222:225], v160 offset:4096
	s_waitcnt lgkmcnt(4)
	v_mfma_f32_32x32x16_bf16 v[48:63], v[164:167], v[172:175], v[48:63]
	v_mfma_f32_32x32x16_bf16 v[32:47], v[164:167], v[176:179], v[32:47]
	v_mfma_f32_32x32x16_bf16 v[16:31], v[168:171], v[172:175], v[16:31]
	v_mfma_f32_32x32x16_bf16 v[0:15], v[168:171], v[176:179], v[0:15]
	s_waitcnt vmcnt(0) lgkmcnt(0)
	s_barrier
	ds_read_b128 v[164:167], v144
	ds_read_b128 v[168:171], v144 offset:4096
	ds_read_b128 v[172:175], v148
	ds_read_b128 v[176:179], v148 offset:4096
	v_mfma_f32_32x32x16_bf16 v[48:63], v[180:183], v[218:221], v[48:63]
	v_mfma_f32_32x32x16_bf16 v[32:47], v[180:183], v[222:225], v[32:47]
	v_mfma_f32_32x32x16_bf16 v[16:31], v[184:187], v[218:221], v[16:31]
	v_mfma_f32_32x32x16_bf16 v[0:15], v[184:187], v[222:225], v[0:15]
	ds_read_b128 v[180:183], v145
	ds_read_b128 v[184:187], v145 offset:4096
	ds_read_b128 v[218:221], v149
	ds_read_b128 v[222:225], v149 offset:4096
	s_waitcnt lgkmcnt(4)
	v_mfma_f32_32x32x16_bf16 v[48:63], v[164:167], v[172:175], v[48:63]
	v_mfma_f32_32x32x16_bf16 v[32:47], v[164:167], v[176:179], v[32:47]
	v_mfma_f32_32x32x16_bf16 v[16:31], v[168:171], v[172:175], v[16:31]
	v_mfma_f32_32x32x16_bf16 v[0:15], v[168:171], v[176:179], v[0:15]
	ds_read_b128 v[164:167], v146
	ds_read_b128 v[168:171], v146 offset:4096
	ds_read_b128 v[172:175], v150
	ds_read_b128 v[176:179], v150 offset:4096
	s_waitcnt lgkmcnt(4)
	v_mfma_f32_32x32x16_bf16 v[48:63], v[180:183], v[218:221], v[48:63]
	v_mfma_f32_32x32x16_bf16 v[32:47], v[180:183], v[222:225], v[32:47]
	v_mfma_f32_32x32x16_bf16 v[16:31], v[184:187], v[218:221], v[16:31]
	v_mfma_f32_32x32x16_bf16 v[0:15], v[184:187], v[222:225], v[0:15]
	ds_read_b128 v[180:183], v147
	ds_read_b128 v[184:187], v147 offset:4096
	ds_read_b128 v[218:221], v151
	ds_read_b128 v[222:225], v151 offset:4096
	s_waitcnt lgkmcnt(4)
	v_mfma_f32_32x32x16_bf16 v[48:63], v[164:167], v[172:175], v[48:63]
	v_mfma_f32_32x32x16_bf16 v[32:47], v[164:167], v[176:179], v[32:47]
	v_mfma_f32_32x32x16_bf16 v[16:31], v[168:171], v[172:175], v[16:31]
	v_mfma_f32_32x32x16_bf16 v[0:15], v[168:171], v[176:179], v[0:15]
	s_waitcnt lgkmcnt(0)
	v_mfma_f32_32x32x16_bf16 v[48:63], v[180:183], v[218:221], v[48:63]
	v_mfma_f32_32x32x16_bf16 v[32:47], v[180:183], v[222:225], v[32:47]
	v_mfma_f32_32x32x16_bf16 v[16:31], v[184:187], v[218:221], v[16:31]
	v_mfma_f32_32x32x16_bf16 v[0:15], v[184:187], v[222:225], v[0:15]
	s_cmp_eq_u32 s11, 1
	s_mov_b32 s26, 0x1810000
	s_movk_i32 s24, 0x100
	s_cselect_b32 s65, s26, 0x1850000
	s_movk_i32 s26, 0x180
	s_cselect_b32 s64, s24, 0x80
	s_cselect_b32 s26, s26, 0x280
	s_nop 15
	s_cmp_eq_u32 s11, 0
	v_mul_f32_e32 v48, 0xbfb8aa3b, v48
	v_exp_f32_e32 v48, v48
	v_mul_f32_e32 v49, 0xbfb8aa3b, v49
	v_exp_f32_e32 v49, v49
	v_mul_f32_e32 v50, 0xbfb8aa3b, v50
	v_add_f32_e32 v48, 1.0, v48
	v_div_scale_f32 v130, s[30:31], v48, v48, 1.0
	v_rcp_f32_e32 v132, v130
	v_add_f32_e32 v49, 1.0, v49
	v_exp_f32_e32 v50, v50
	v_mul_f32_e32 v51, 0xbfb8aa3b, v51
	v_fma_f32 v133, -v130, v132, 1.0
	v_fmac_f32_e32 v132, v133, v132
	v_div_scale_f32 v133, vcc, 1.0, v48, 1.0
	v_mul_f32_e32 v134, v133, v132
	v_fma_f32 v135, -v130, v134, v133
	v_fmac_f32_e32 v134, v135, v132
	v_fma_f32 v130, -v130, v134, v133
	v_div_scale_f32 v133, s[30:31], v49, v49, 1.0
	v_rcp_f32_e32 v135, v133
	v_div_fmas_f32 v130, v130, v132, v134
	v_div_fixup_f32 v48, v130, v48, 1.0
	v_add_f32_e32 v50, 1.0, v50
	v_fma_f32 v130, -v133, v135, 1.0
	v_fmac_f32_e32 v135, v130, v135
	v_div_scale_f32 v130, vcc, 1.0, v49, 1.0
	v_mul_f32_e32 v132, v130, v135
	v_fma_f32 v134, -v133, v132, v130
	v_fmac_f32_e32 v132, v134, v135
	v_fma_f32 v130, -v133, v132, v130
	v_div_scale_f32 v133, s[30:31], v50, v50, 1.0
	v_rcp_f32_e32 v134, v133
	v_div_fmas_f32 v130, v130, v135, v132
	v_exp_f32_e32 v51, v51
	v_div_fixup_f32 v49, v130, v49, 1.0
	v_cvt_pk_bf16_f32 v144, v48, v49
	v_fma_f32 v48, -v133, v134, 1.0
	v_fmac_f32_e32 v134, v48, v134
	v_div_scale_f32 v48, vcc, 1.0, v50, 1.0
	v_mul_f32_e32 v49, v48, v134
	v_fma_f32 v130, -v133, v49, v48
	v_add_f32_e32 v51, 1.0, v51
	v_fmac_f32_e32 v49, v130, v134
	v_div_scale_f32 v130, s[30:31], v51, v51, 1.0
	v_rcp_f32_e32 v132, v130
	v_fma_f32 v48, -v133, v49, v48
	v_mul_f32_e32 v52, 0xbfb8aa3b, v52
; DI unsigned pack2(float a, float b) { unsigned r; asm("v_cvt_pk_bf16_f32 %0, %1, %2" : "=v"(r) : "v"(a), "v"(b)); return r; }
; DI float sigmoidf_(float x) { return 1.f / (1.f + __expf(-x)); }
; DI void merge_phase(const Params& p, int layer, char* lds) {
;     ...
; #pragma unroll
;         for (int a = 0; a < 2; ++a)
; #pragma unroll
;           for (int c = 0; c < 2; ++c)
; #pragma unroll
;             for (int i = 0; i < 8; ++i) sg[a][c][i] = pack2(sigmoidf_(ag[a][c][2 * i]), sigmoidf_(ag[a][c][2 * i + 1]));
	v_div_fmas_f32 v48, v48, v134, v49
	v_fma_f32 v49, -v130, v132, 1.0
	v_exp_f32_e32 v52, v52
	v_fmac_f32_e32 v132, v49, v132
	v_div_scale_f32 v49, vcc, 1.0, v51, 1.0
	v_div_fixup_f32 v48, v48, v50, 1.0
	v_mul_f32_e32 v50, v49, v132
	v_fma_f32 v133, -v130, v50, v49
	v_fmac_f32_e32 v50, v133, v132
	v_add_f32_e32 v52, 1.0, v52
	v_fma_f32 v49, -v130, v50, v49
	v_div_scale_f32 v130, s[30:31], v52, v52, 1.0
	v_rcp_f32_e32 v133, v130
	v_div_fmas_f32 v49, v49, v132, v50
	v_mul_f32_e32 v50, 0xbfb8aa3b, v53
	v_exp_f32_e32 v50, v50
	v_div_fixup_f32 v49, v49, v51, 1.0
	v_cvt_pk_bf16_f32 v145, v48, v49
	v_fma_f32 v48, -v130, v133, 1.0
	v_fmac_f32_e32 v133, v48, v133
	v_div_scale_f32 v48, vcc, 1.0, v52, 1.0
	v_mul_f32_e32 v49, v48, v133
	v_fma_f32 v51, -v130, v49, v48
	v_add_f32_e32 v50, 1.0, v50
	v_fmac_f32_e32 v49, v51, v133
	v_div_scale_f32 v51, s[30:31], v50, v50, 1.0
	v_rcp_f32_e32 v53, v51
	v_fma_f32 v48, -v130, v49, v48
	v_div_fmas_f32 v48, v48, v133, v49
	v_mul_f32_e32 v54, 0xbfb8aa3b, v54
	v_fma_f32 v49, -v51, v53, 1.0
	v_fmac_f32_e32 v53, v49, v53
	v_div_scale_f32 v49, vcc, 1.0, v50, 1.0
	v_exp_f32_e32 v54, v54
	v_div_fixup_f32 v48, v48, v52, 1.0
	v_mul_f32_e32 v52, v49, v53
	v_fma_f32 v130, -v51, v52, v49
	v_fmac_f32_e32 v52, v130, v53
	v_fma_f32 v49, -v51, v52, v49
	v_add_f32_e32 v51, 1.0, v54
	v_div_scale_f32 v54, s[30:31], v51, v51, 1.0
	v_rcp_f32_e32 v130, v54
	v_div_fmas_f32 v49, v49, v53, v52
	v_div_fixup_f32 v49, v49, v50, 1.0
	v_mul_f32_e32 v50, 0xbfb8aa3b, v55
	v_exp_f32_e32 v50, v50
	v_cvt_pk_bf16_f32 v146, v48, v49
	v_fma_f32 v48, -v54, v130, 1.0
	v_fmac_f32_e32 v130, v48, v130
	v_div_scale_f32 v48, vcc, 1.0, v51, 1.0
	v_mul_f32_e32 v49, v48, v130
	v_fma_f32 v52, -v54, v49, v48
	v_add_f32_e32 v50, 1.0, v50
	v_fmac_f32_e32 v49, v52, v130
	v_div_scale_f32 v52, s[30:31], v50, v50, 1.0
	v_rcp_f32_e32 v53, v52
	v_fma_f32 v48, -v54, v49, v48
	v_div_fmas_f32 v48, v48, v130, v49
	v_mul_f32_e32 v54, 0xbfb8aa3b, v56
	v_fma_f32 v49, -v52, v53, 1.0
	v_fmac_f32_e32 v53, v49, v53
	v_div_scale_f32 v49, vcc, 1.0, v50, 1.0
	v_exp_f32_e32 v54, v54
	v_div_fixup_f32 v48, v48, v51, 1.0
	v_mul_f32_e32 v51, v49, v53
	v_fma_f32 v55, -v52, v51, v49
	v_fmac_f32_e32 v51, v55, v53
	v_fma_f32 v49, -v52, v51, v49
	v_add_f32_e32 v52, 1.0, v54
	v_div_scale_f32 v54, s[30:31], v52, v52, 1.0
	v_rcp_f32_e32 v55, v54
	v_div_fmas_f32 v49, v49, v53, v51
	v_div_fixup_f32 v49, v49, v50, 1.0
	v_mul_f32_e32 v50, 0xbfb8aa3b, v57
	v_exp_f32_e32 v50, v50
	v_cvt_pk_bf16_f32 v147, v48, v49
	v_fma_f32 v48, -v54, v55, 1.0
	v_fmac_f32_e32 v55, v48, v55
	v_div_scale_f32 v48, vcc, 1.0, v52, 1.0
	v_mul_f32_e32 v49, v48, v55
	v_fma_f32 v51, -v54, v49, v48
	v_add_f32_e32 v50, 1.0, v50
	v_fmac_f32_e32 v49, v51, v55
	v_div_scale_f32 v51, s[30:31], v50, v50, 1.0
	v_rcp_f32_e32 v53, v51
	v_fma_f32 v48, -v54, v49, v48
	v_div_fmas_f32 v48, v48, v55, v49
	v_mul_f32_e32 v54, 0xbfb8aa3b, v58
	v_fma_f32 v49, -v51, v53, 1.0
	v_fmac_f32_e32 v53, v49, v53
	v_div_scale_f32 v49, vcc, 1.0, v50, 1.0
	v_exp_f32_e32 v54, v54
	v_div_fixup_f32 v48, v48, v52, 1.0
	v_mul_f32_e32 v52, v49, v53
	v_fma_f32 v55, -v51, v52, v49
	v_fmac_f32_e32 v52, v55, v53
	v_fma_f32 v49, -v51, v52, v49
	v_add_f32_e32 v51, 1.0, v54
	v_div_scale_f32 v54, s[30:31], v51, v51, 1.0
	v_rcp_f32_e32 v55, v54
	v_div_fmas_f32 v49, v49, v53, v52
	v_div_fixup_f32 v49, v49, v50, 1.0
	v_mul_f32_e32 v50, 0xbfb8aa3b, v59
	v_exp_f32_e32 v50, v50
	v_cvt_pk_bf16_f32 v148, v48, v49
	v_fma_f32 v48, -v54, v55, 1.0
	v_fmac_f32_e32 v55, v48, v55
	v_div_scale_f32 v48, vcc, 1.0, v51, 1.0
	v_mul_f32_e32 v49, v48, v55
	v_fma_f32 v52, -v54, v49, v48
	v_add_f32_e32 v50, 1.0, v50
	v_fmac_f32_e32 v49, v52, v55
	v_div_scale_f32 v52, s[30:31], v50, v50, 1.0
	v_rcp_f32_e32 v53, v52
	v_fma_f32 v48, -v54, v49, v48
	v_div_fmas_f32 v48, v48, v55, v49
	v_mul_f32_e32 v54, 0xbfb8aa3b, v60
	v_fma_f32 v49, -v52, v53, 1.0
	v_fmac_f32_e32 v53, v49, v53
	v_div_scale_f32 v49, vcc, 1.0, v50, 1.0
	v_exp_f32_e32 v54, v54
	v_div_fixup_f32 v48, v48, v51, 1.0
	v_mul_f32_e32 v51, v49, v53
	v_fma_f32 v55, -v52, v51, v49
	v_fmac_f32_e32 v51, v55, v53
	v_fma_f32 v49, -v52, v51, v49
	v_add_f32_e32 v52, 1.0, v54
	v_div_scale_f32 v54, s[30:31], v52, v52, 1.0
	v_rcp_f32_e32 v55, v54
	v_div_fmas_f32 v49, v49, v53, v51
	v_div_fixup_f32 v49, v49, v50, 1.0
	v_mul_f32_e32 v50, 0xbfb8aa3b, v61
	v_exp_f32_e32 v50, v50
	v_cvt_pk_bf16_f32 v149, v48, v49
	v_fma_f32 v48, -v54, v55, 1.0
	v_fmac_f32_e32 v55, v48, v55
	v_div_scale_f32 v48, vcc, 1.0, v52, 1.0
	v_mul_f32_e32 v49, v48, v55
	v_fma_f32 v51, -v54, v49, v48
	v_add_f32_e32 v50, 1.0, v50
	v_fmac_f32_e32 v49, v51, v55
	v_div_scale_f32 v51, s[30:31], v50, v50, 1.0
	v_rcp_f32_e32 v53, v51
	v_fma_f32 v48, -v54, v49, v48
	v_div_fmas_f32 v48, v48, v55, v49
	v_mul_f32_e32 v54, 0xbfb8aa3b, v62
	v_fma_f32 v49, -v51, v53, 1.0
	v_fmac_f32_e32 v53, v49, v53
	v_div_scale_f32 v49, vcc, 1.0, v50, 1.0
	v_exp_f32_e32 v54, v54
	v_div_fixup_f32 v48, v48, v52, 1.0
	v_mul_f32_e32 v52, v49, v53
	v_fma_f32 v55, -v51, v52, v49
	v_fmac_f32_e32 v52, v55, v53
	v_fma_f32 v49, -v51, v52, v49
	v_add_f32_e32 v51, 1.0, v54
	v_div_scale_f32 v54, s[30:31], v51, v51, 1.0
	v_rcp_f32_e32 v55, v54
	v_div_fmas_f32 v49, v49, v53, v52
	v_div_fixup_f32 v49, v49, v50, 1.0
	v_mul_f32_e32 v50, 0xbfb8aa3b, v63
	v_exp_f32_e32 v50, v50
	v_cvt_pk_bf16_f32 v150, v48, v49
	v_fma_f32 v48, -v54, v55, 1.0
	v_fmac_f32_e32 v55, v48, v55
	v_div_scale_f32 v48, vcc, 1.0, v51, 1.0
	v_mul_f32_e32 v49, v48, v55
	v_fma_f32 v52, -v54, v49, v48
	v_add_f32_e32 v50, 1.0, v50
	v_fmac_f32_e32 v49, v52, v55
	v_div_scale_f32 v52, s[30:31], v50, v50, 1.0
	v_rcp_f32_e32 v53, v52
	v_fma_f32 v48, -v54, v49, v48
; DI unsigned pack2(float a, float b) { unsigned r; asm("v_cvt_pk_bf16_f32 %0, %1, %2" : "=v"(r) : "v"(a), "v"(b)); return r; }
; DI float sigmoidf_(float x) { return 1.f / (1.f + __expf(-x)); }
; DI void merge_phase(const Params& p, int layer, char* lds) {
;     ...
; #pragma unroll
;         for (int a = 0; a < 2; ++a)
; #pragma unroll
;           for (int c = 0; c < 2; ++c)
; #pragma unroll
;             for (int i = 0; i < 8; ++i) sg[a][c][i] = pack2(sigmoidf_(ag[a][c][2 * i]), sigmoidf_(ag[a][c][2 * i + 1]));
	v_mul_f32_e32 v32, 0xbfb8aa3b, v32
	v_div_fmas_f32 v48, v48, v55, v49
	v_fma_f32 v49, -v52, v53, 1.0
	v_exp_f32_e32 v32, v32
	v_fmac_f32_e32 v53, v49, v53
	v_div_scale_f32 v49, vcc, 1.0, v50, 1.0
	v_div_fixup_f32 v48, v48, v51, 1.0
	v_mul_f32_e32 v51, v49, v53
	v_fma_f32 v54, -v52, v51, v49
	v_fmac_f32_e32 v51, v54, v53
	v_add_f32_e32 v32, 1.0, v32
	v_fma_f32 v49, -v52, v51, v49
	v_div_scale_f32 v52, s[30:31], v32, v32, 1.0
	v_rcp_f32_e32 v54, v52
	v_mul_f32_e32 v33, 0xbfb8aa3b, v33
	v_div_fmas_f32 v49, v49, v53, v51
	v_exp_f32_e32 v33, v33
	v_div_fixup_f32 v49, v49, v50, 1.0
	v_cvt_pk_bf16_f32 v151, v48, v49
	v_fma_f32 v48, -v52, v54, 1.0
	v_fmac_f32_e32 v54, v48, v54
	v_div_scale_f32 v48, vcc, 1.0, v32, 1.0
	v_mul_f32_e32 v49, v48, v54
	v_fma_f32 v50, -v52, v49, v48
	v_add_f32_e32 v33, 1.0, v33
	v_fmac_f32_e32 v49, v50, v54
	v_div_scale_f32 v50, s[30:31], v33, v33, 1.0
	v_rcp_f32_e32 v51, v50
	v_fma_f32 v48, -v52, v49, v48
	v_div_fmas_f32 v48, v48, v54, v49
	v_mul_f32_e32 v34, 0xbfb8aa3b, v34
	v_div_fixup_f32 v32, v48, v32, 1.0
	v_fma_f32 v48, -v50, v51, 1.0
	v_exp_f32_e32 v34, v34
	v_fmac_f32_e32 v51, v48, v51
	v_div_scale_f32 v48, vcc, 1.0, v33, 1.0
	v_mul_f32_e32 v49, v48, v51
	v_fma_f32 v52, -v50, v49, v48
	v_fmac_f32_e32 v49, v52, v51
	v_add_f32_e32 v34, 1.0, v34
	v_fma_f32 v48, -v50, v49, v48
	v_div_scale_f32 v50, s[30:31], v34, v34, 1.0
	v_rcp_f32_e32 v52, v50
	v_mul_f32_e32 v35, 0xbfb8aa3b, v35
	v_div_fmas_f32 v48, v48, v51, v49
	v_exp_f32_e32 v35, v35
	v_div_fixup_f32 v33, v48, v33, 1.0
	v_cvt_pk_bf16_f32 v152, v32, v33
	v_fma_f32 v32, -v50, v52, 1.0
	v_fmac_f32_e32 v52, v32, v52
	v_div_scale_f32 v32, vcc, 1.0, v34, 1.0
	v_mul_f32_e32 v33, v32, v52
	v_fma_f32 v48, -v50, v33, v32
	v_add_f32_e32 v35, 1.0, v35
	v_fmac_f32_e32 v33, v48, v52
	v_div_scale_f32 v48, s[30:31], v35, v35, 1.0
	v_rcp_f32_e32 v49, v48
	v_fma_f32 v32, -v50, v33, v32
	v_mul_f32_e32 v36, 0xbfb8aa3b, v36
	v_div_fmas_f32 v32, v32, v52, v33
	v_fma_f32 v33, -v48, v49, 1.0
	v_exp_f32_e32 v36, v36
	v_fmac_f32_e32 v49, v33, v49
	v_div_scale_f32 v33, vcc, 1.0, v35, 1.0
	v_div_fixup_f32 v32, v32, v34, 1.0
	v_mul_f32_e32 v34, v33, v49
	v_fma_f32 v50, -v48, v34, v33
	v_fmac_f32_e32 v34, v50, v49
	v_add_f32_e32 v36, 1.0, v36
	v_fma_f32 v33, -v48, v34, v33
	v_div_scale_f32 v48, s[30:31], v36, v36, 1.0
	v_rcp_f32_e32 v50, v48
	v_div_fmas_f32 v33, v33, v49, v34
	v_mul_f32_e32 v34, 0xbfb8aa3b, v37
	v_exp_f32_e32 v34, v34
	v_div_fixup_f32 v33, v33, v35, 1.0
	v_cvt_pk_bf16_f32 v153, v32, v33
	v_fma_f32 v32, -v48, v50, 1.0
	v_fmac_f32_e32 v50, v32, v50
	v_div_scale_f32 v32, vcc, 1.0, v36, 1.0
	v_mul_f32_e32 v33, v32, v50
	v_fma_f32 v35, -v48, v33, v32
	v_add_f32_e32 v34, 1.0, v34
	v_fmac_f32_e32 v33, v35, v50
	v_div_scale_f32 v35, s[30:31], v34, v34, 1.0
	v_rcp_f32_e32 v37, v35
	v_fma_f32 v32, -v48, v33, v32
	v_div_fmas_f32 v32, v32, v50, v33
	v_mul_f32_e32 v38, 0xbfb8aa3b, v38
	v_fma_f32 v33, -v35, v37, 1.0
	v_fmac_f32_e32 v37, v33, v37
	v_div_scale_f32 v33, vcc, 1.0, v34, 1.0
	v_exp_f32_e32 v38, v38
	v_div_fixup_f32 v32, v32, v36, 1.0
	v_mul_f32_e32 v36, v33, v37
	v_fma_f32 v48, -v35, v36, v33
	v_fmac_f32_e32 v36, v48, v37
	v_fma_f32 v33, -v35, v36, v33
	v_add_f32_e32 v35, 1.0, v38
	v_div_scale_f32 v38, s[30:31], v35, v35, 1.0
	v_rcp_f32_e32 v48, v38
	v_div_fmas_f32 v33, v33, v37, v36
	v_div_fixup_f32 v33, v33, v34, 1.0
	v_mul_f32_e32 v34, 0xbfb8aa3b, v39
	v_exp_f32_e32 v34, v34
	v_cvt_pk_bf16_f32 v154, v32, v33
	v_fma_f32 v32, -v38, v48, 1.0
	v_fmac_f32_e32 v48, v32, v48
	v_div_scale_f32 v32, vcc, 1.0, v35, 1.0
	v_mul_f32_e32 v33, v32, v48
	v_fma_f32 v36, -v38, v33, v32
	v_add_f32_e32 v34, 1.0, v34
	v_fmac_f32_e32 v33, v36, v48
	v_div_scale_f32 v36, s[30:31], v34, v34, 1.0
	v_rcp_f32_e32 v37, v36
	v_fma_f32 v32, -v38, v33, v32
	v_div_fmas_f32 v32, v32, v48, v33
	v_mul_f32_e32 v38, 0xbfb8aa3b, v40
	v_fma_f32 v33, -v36, v37, 1.0
	v_fmac_f32_e32 v37, v33, v37
	v_div_scale_f32 v33, vcc, 1.0, v34, 1.0
	v_exp_f32_e32 v38, v38
	v_div_fixup_f32 v32, v32, v35, 1.0
	v_mul_f32_e32 v35, v33, v37
	v_fma_f32 v39, -v36, v35, v33
	v_fmac_f32_e32 v35, v39, v37
	v_fma_f32 v33, -v36, v35, v33
	v_add_f32_e32 v36, 1.0, v38
	v_div_scale_f32 v38, s[30:31], v36, v36, 1.0
	v_rcp_f32_e32 v39, v38
	v_div_fmas_f32 v33, v33, v37, v35
	v_div_fixup_f32 v33, v33, v34, 1.0
	v_mul_f32_e32 v34, 0xbfb8aa3b, v41
	v_exp_f32_e32 v34, v34
	v_cvt_pk_bf16_f32 v155, v32, v33
	v_fma_f32 v32, -v38, v39, 1.0
	v_fmac_f32_e32 v39, v32, v39
	v_div_scale_f32 v32, vcc, 1.0, v36, 1.0
	v_mul_f32_e32 v33, v32, v39
	v_fma_f32 v35, -v38, v33, v32
	v_add_f32_e32 v34, 1.0, v34
	v_fmac_f32_e32 v33, v35, v39
	v_div_scale_f32 v35, s[30:31], v34, v34, 1.0
	v_rcp_f32_e32 v37, v35
	v_fma_f32 v32, -v38, v33, v32
	v_div_fmas_f32 v32, v32, v39, v33
	v_mul_f32_e32 v38, 0xbfb8aa3b, v42
	v_fma_f32 v33, -v35, v37, 1.0
	v_fmac_f32_e32 v37, v33, v37
	v_div_scale_f32 v33, vcc, 1.0, v34, 1.0
	v_exp_f32_e32 v38, v38
	v_div_fixup_f32 v32, v32, v36, 1.0
	v_mul_f32_e32 v36, v33, v37
	v_fma_f32 v39, -v35, v36, v33
	v_fmac_f32_e32 v36, v39, v37
	v_fma_f32 v33, -v35, v36, v33
	v_add_f32_e32 v35, 1.0, v38
	v_div_scale_f32 v38, s[30:31], v35, v35, 1.0
	v_rcp_f32_e32 v39, v38
	v_div_fmas_f32 v33, v33, v37, v36
	v_div_fixup_f32 v33, v33, v34, 1.0
	v_mul_f32_e32 v34, 0xbfb8aa3b, v43
	v_exp_f32_e32 v34, v34
	v_cvt_pk_bf16_f32 v157, v32, v33
	v_fma_f32 v32, -v38, v39, 1.0
	v_fmac_f32_e32 v39, v32, v39
	v_div_scale_f32 v32, vcc, 1.0, v35, 1.0
	v_mul_f32_e32 v33, v32, v39
	v_fma_f32 v36, -v38, v33, v32
	v_add_f32_e32 v34, 1.0, v34
	v_fmac_f32_e32 v33, v36, v39
	v_div_scale_f32 v36, s[30:31], v34, v34, 1.0
	v_rcp_f32_e32 v37, v36
	v_fma_f32 v32, -v38, v33, v32
; DI unsigned pack2(float a, float b) { unsigned r; asm("v_cvt_pk_bf16_f32 %0, %1, %2" : "=v"(r) : "v"(a), "v"(b)); return r; }
; DI float sigmoidf_(float x) { return 1.f / (1.f + __expf(-x)); }
; DI void merge_phase(const Params& p, int layer, char* lds) {
;     ...
; #pragma unroll
;         for (int a = 0; a < 2; ++a)
; #pragma unroll
;           for (int c = 0; c < 2; ++c)
; #pragma unroll
;             for (int i = 0; i < 8; ++i) sg[a][c][i] = pack2(sigmoidf_(ag[a][c][2 * i]), sigmoidf_(ag[a][c][2 * i + 1]));
	v_div_fmas_f32 v32, v32, v39, v33
	v_mul_f32_e32 v38, 0xbfb8aa3b, v44
	v_fma_f32 v33, -v36, v37, 1.0
	v_fmac_f32_e32 v37, v33, v37
	v_div_scale_f32 v33, vcc, 1.0, v34, 1.0
	v_exp_f32_e32 v38, v38
	v_div_fixup_f32 v32, v32, v35, 1.0
	v_mul_f32_e32 v35, v33, v37
	v_fma_f32 v39, -v36, v35, v33
	v_fmac_f32_e32 v35, v39, v37
	v_fma_f32 v33, -v36, v35, v33
	v_add_f32_e32 v36, 1.0, v38
	v_div_scale_f32 v38, s[30:31], v36, v36, 1.0
	v_rcp_f32_e32 v39, v38
	v_div_fmas_f32 v33, v33, v37, v35
	v_div_fixup_f32 v33, v33, v34, 1.0
	v_mul_f32_e32 v34, 0xbfb8aa3b, v45
	v_exp_f32_e32 v34, v34
	v_cvt_pk_bf16_f32 v158, v32, v33
	v_fma_f32 v32, -v38, v39, 1.0
	v_fmac_f32_e32 v39, v32, v39
	v_div_scale_f32 v32, vcc, 1.0, v36, 1.0
	v_mul_f32_e32 v33, v32, v39
	v_fma_f32 v35, -v38, v33, v32
	v_add_f32_e32 v34, 1.0, v34
	v_fmac_f32_e32 v33, v35, v39
	v_div_scale_f32 v35, s[30:31], v34, v34, 1.0
	v_rcp_f32_e32 v37, v35
	v_fma_f32 v32, -v38, v33, v32
	v_div_fmas_f32 v32, v32, v39, v33
	v_mul_f32_e32 v38, 0xbfb8aa3b, v46
	v_fma_f32 v33, -v35, v37, 1.0
	v_fmac_f32_e32 v37, v33, v37
	v_div_scale_f32 v33, vcc, 1.0, v34, 1.0
	v_exp_f32_e32 v38, v38
	v_div_fixup_f32 v32, v32, v36, 1.0
	v_mul_f32_e32 v36, v33, v37
	v_fma_f32 v39, -v35, v36, v33
	v_fmac_f32_e32 v36, v39, v37
	v_fma_f32 v33, -v35, v36, v33
	v_add_f32_e32 v35, 1.0, v38
	v_div_scale_f32 v38, s[30:31], v35, v35, 1.0
	v_rcp_f32_e32 v39, v38
	v_div_fmas_f32 v33, v33, v37, v36
	v_div_fixup_f32 v33, v33, v34, 1.0
	v_mul_f32_e32 v34, 0xbfb8aa3b, v47
	v_exp_f32_e32 v34, v34
	v_cvt_pk_bf16_f32 v159, v32, v33
	v_fma_f32 v32, -v38, v39, 1.0
	v_fmac_f32_e32 v39, v32, v39
	v_div_scale_f32 v32, vcc, 1.0, v35, 1.0
	v_mul_f32_e32 v33, v32, v39
	v_fma_f32 v36, -v38, v33, v32
	v_add_f32_e32 v34, 1.0, v34
	v_fmac_f32_e32 v33, v36, v39
	v_div_scale_f32 v36, s[30:31], v34, v34, 1.0
	v_rcp_f32_e32 v37, v36
	v_fma_f32 v32, -v38, v33, v32
	v_mul_f32_e32 v16, 0xbfb8aa3b, v16
	v_div_fmas_f32 v32, v32, v39, v33
	v_fma_f32 v33, -v36, v37, 1.0
	v_exp_f32_e32 v16, v16
	v_fmac_f32_e32 v37, v33, v37
	v_div_scale_f32 v33, vcc, 1.0, v34, 1.0
	v_div_fixup_f32 v32, v32, v35, 1.0
	v_mul_f32_e32 v35, v33, v37
	v_fma_f32 v38, -v36, v35, v33
	v_fmac_f32_e32 v35, v38, v37
	v_add_f32_e32 v16, 1.0, v16
	v_fma_f32 v33, -v36, v35, v33
	v_div_scale_f32 v36, s[30:31], v16, v16, 1.0
	v_rcp_f32_e32 v38, v36
	v_mul_f32_e32 v17, 0xbfb8aa3b, v17
	v_div_fmas_f32 v33, v33, v37, v35
	v_exp_f32_e32 v17, v17
	v_div_fixup_f32 v33, v33, v34, 1.0
	v_cvt_pk_bf16_f32 v160, v32, v33
	v_fma_f32 v32, -v36, v38, 1.0
	v_fmac_f32_e32 v38, v32, v38
	v_div_scale_f32 v32, vcc, 1.0, v16, 1.0
	v_mul_f32_e32 v33, v32, v38
	v_fma_f32 v34, -v36, v33, v32
	v_add_f32_e32 v17, 1.0, v17
	v_fmac_f32_e32 v33, v34, v38
	v_div_scale_f32 v34, s[30:31], v17, v17, 1.0
	v_rcp_f32_e32 v35, v34
	v_fma_f32 v32, -v36, v33, v32
	v_div_fmas_f32 v32, v32, v38, v33
	v_mul_f32_e32 v18, 0xbfb8aa3b, v18
	v_div_fixup_f32 v16, v32, v16, 1.0
	v_fma_f32 v32, -v34, v35, 1.0
	v_exp_f32_e32 v18, v18
	v_fmac_f32_e32 v35, v32, v35
	v_div_scale_f32 v32, vcc, 1.0, v17, 1.0
	v_mul_f32_e32 v33, v32, v35
	v_fma_f32 v36, -v34, v33, v32
	v_fmac_f32_e32 v33, v36, v35
	v_add_f32_e32 v18, 1.0, v18
	v_fma_f32 v32, -v34, v33, v32
	v_div_scale_f32 v34, s[30:31], v18, v18, 1.0
	v_rcp_f32_e32 v36, v34
	v_mul_f32_e32 v19, 0xbfb8aa3b, v19
	v_div_fmas_f32 v32, v32, v35, v33
	v_exp_f32_e32 v19, v19
	v_div_fixup_f32 v17, v32, v17, 1.0
	v_cvt_pk_bf16_f32 v161, v16, v17
	v_fma_f32 v16, -v34, v36, 1.0
	v_fmac_f32_e32 v36, v16, v36
	v_div_scale_f32 v16, vcc, 1.0, v18, 1.0
	v_mul_f32_e32 v17, v16, v36
	v_fma_f32 v32, -v34, v17, v16
	v_add_f32_e32 v19, 1.0, v19
	v_fmac_f32_e32 v17, v32, v36
	v_div_scale_f32 v32, s[30:31], v19, v19, 1.0
	v_rcp_f32_e32 v33, v32
	v_fma_f32 v16, -v34, v17, v16
	v_mul_f32_e32 v20, 0xbfb8aa3b, v20
	v_div_fmas_f32 v16, v16, v36, v17
	v_fma_f32 v17, -v32, v33, 1.0
	v_exp_f32_e32 v20, v20
	v_fmac_f32_e32 v33, v17, v33
	v_div_scale_f32 v17, vcc, 1.0, v19, 1.0
	v_div_fixup_f32 v16, v16, v18, 1.0
	v_mul_f32_e32 v18, v17, v33
	v_fma_f32 v34, -v32, v18, v17
	v_fmac_f32_e32 v18, v34, v33
	v_add_f32_e32 v20, 1.0, v20
	v_fma_f32 v17, -v32, v18, v17
	v_div_scale_f32 v32, s[30:31], v20, v20, 1.0
	v_rcp_f32_e32 v34, v32
	v_div_fmas_f32 v17, v17, v33, v18
	v_mul_f32_e32 v18, 0xbfb8aa3b, v21
	v_exp_f32_e32 v18, v18
	v_div_fixup_f32 v17, v17, v19, 1.0
	v_cvt_pk_bf16_f32 v162, v16, v17
	v_fma_f32 v16, -v32, v34, 1.0
	v_fmac_f32_e32 v34, v16, v34
	v_div_scale_f32 v16, vcc, 1.0, v20, 1.0
	v_mul_f32_e32 v17, v16, v34
	v_fma_f32 v19, -v32, v17, v16
	v_add_f32_e32 v18, 1.0, v18
	v_fmac_f32_e32 v17, v19, v34
	v_div_scale_f32 v19, s[30:31], v18, v18, 1.0
	v_rcp_f32_e32 v21, v19
	v_fma_f32 v16, -v32, v17, v16
	v_div_fmas_f32 v16, v16, v34, v17
	v_mul_f32_e32 v22, 0xbfb8aa3b, v22
	v_fma_f32 v17, -v19, v21, 1.0
	v_fmac_f32_e32 v21, v17, v21
	v_div_scale_f32 v17, vcc, 1.0, v18, 1.0
	v_exp_f32_e32 v22, v22
	v_div_fixup_f32 v16, v16, v20, 1.0
	v_mul_f32_e32 v20, v17, v21
	v_fma_f32 v32, -v19, v20, v17
	v_fmac_f32_e32 v20, v32, v21
	v_fma_f32 v17, -v19, v20, v17
	v_add_f32_e32 v19, 1.0, v22
	v_div_scale_f32 v22, s[30:31], v19, v19, 1.0
	v_rcp_f32_e32 v32, v22
	v_div_fmas_f32 v17, v17, v21, v20
	v_div_fixup_f32 v17, v17, v18, 1.0
	v_mul_f32_e32 v18, 0xbfb8aa3b, v23
	v_exp_f32_e32 v18, v18
	v_cvt_pk_bf16_f32 v163, v16, v17
	v_fma_f32 v16, -v22, v32, 1.0
	v_fmac_f32_e32 v32, v16, v32
	v_div_scale_f32 v16, vcc, 1.0, v19, 1.0
	v_mul_f32_e32 v17, v16, v32
	v_fma_f32 v20, -v22, v17, v16
	v_add_f32_e32 v18, 1.0, v18
	v_fmac_f32_e32 v17, v20, v32
	v_div_scale_f32 v20, s[30:31], v18, v18, 1.0
	v_rcp_f32_e32 v21, v20
	v_fma_f32 v16, -v22, v17, v16
; DI unsigned pack2(float a, float b) { unsigned r; asm("v_cvt_pk_bf16_f32 %0, %1, %2" : "=v"(r) : "v"(a), "v"(b)); return r; }
; DI float sigmoidf_(float x) { return 1.f / (1.f + __expf(-x)); }
; DI void merge_phase(const Params& p, int layer, char* lds) {
;     ...
; #pragma unroll
;         for (int a = 0; a < 2; ++a)
; #pragma unroll
;           for (int c = 0; c < 2; ++c)
; #pragma unroll
;             for (int i = 0; i < 8; ++i) sg[a][c][i] = pack2(sigmoidf_(ag[a][c][2 * i]), sigmoidf_(ag[a][c][2 * i + 1]));
	v_div_fmas_f32 v16, v16, v32, v17
	v_mul_f32_e32 v22, 0xbfb8aa3b, v24
	v_fma_f32 v17, -v20, v21, 1.0
	v_fmac_f32_e32 v21, v17, v21
	v_div_scale_f32 v17, vcc, 1.0, v18, 1.0
	v_exp_f32_e32 v22, v22
	v_div_fixup_f32 v16, v16, v19, 1.0
	v_mul_f32_e32 v19, v17, v21
	v_fma_f32 v23, -v20, v19, v17
	v_fmac_f32_e32 v19, v23, v21
	v_fma_f32 v17, -v20, v19, v17
	v_add_f32_e32 v20, 1.0, v22
	v_div_scale_f32 v22, s[30:31], v20, v20, 1.0
	v_rcp_f32_e32 v23, v22
	v_div_fmas_f32 v17, v17, v21, v19
	v_div_fixup_f32 v17, v17, v18, 1.0
	v_mul_f32_e32 v18, 0xbfb8aa3b, v25
	v_exp_f32_e32 v18, v18
	v_cvt_pk_bf16_f32 v164, v16, v17
	v_fma_f32 v16, -v22, v23, 1.0
	v_fmac_f32_e32 v23, v16, v23
	v_div_scale_f32 v16, vcc, 1.0, v20, 1.0
	v_mul_f32_e32 v17, v16, v23
	v_fma_f32 v19, -v22, v17, v16
	v_add_f32_e32 v18, 1.0, v18
	v_fmac_f32_e32 v17, v19, v23
	v_div_scale_f32 v19, s[30:31], v18, v18, 1.0
	v_rcp_f32_e32 v21, v19
	v_fma_f32 v16, -v22, v17, v16
	v_div_fmas_f32 v16, v16, v23, v17
	v_mul_f32_e32 v22, 0xbfb8aa3b, v26
	v_fma_f32 v17, -v19, v21, 1.0
	v_fmac_f32_e32 v21, v17, v21
	v_div_scale_f32 v17, vcc, 1.0, v18, 1.0
	v_exp_f32_e32 v22, v22
	v_div_fixup_f32 v16, v16, v20, 1.0
	v_mul_f32_e32 v20, v17, v21
	v_fma_f32 v23, -v19, v20, v17
	v_fmac_f32_e32 v20, v23, v21
	v_fma_f32 v17, -v19, v20, v17
	v_add_f32_e32 v19, 1.0, v22
	v_div_scale_f32 v22, s[30:31], v19, v19, 1.0
	v_rcp_f32_e32 v23, v22
	v_div_fmas_f32 v17, v17, v21, v20
	v_div_fixup_f32 v17, v17, v18, 1.0
	v_mul_f32_e32 v18, 0xbfb8aa3b, v27
	v_exp_f32_e32 v18, v18
	v_cvt_pk_bf16_f32 v165, v16, v17
	v_fma_f32 v16, -v22, v23, 1.0
	v_fmac_f32_e32 v23, v16, v23
	v_div_scale_f32 v16, vcc, 1.0, v19, 1.0
	v_mul_f32_e32 v17, v16, v23
	v_fma_f32 v20, -v22, v17, v16
	v_add_f32_e32 v18, 1.0, v18
	v_fmac_f32_e32 v17, v20, v23
	v_div_scale_f32 v20, s[30:31], v18, v18, 1.0
	v_rcp_f32_e32 v21, v20
	v_fma_f32 v16, -v22, v17, v16
	v_div_fmas_f32 v16, v16, v23, v17
	v_mul_f32_e32 v22, 0xbfb8aa3b, v28
	v_fma_f32 v17, -v20, v21, 1.0
	v_fmac_f32_e32 v21, v17, v21
	v_div_scale_f32 v17, vcc, 1.0, v18, 1.0
	v_exp_f32_e32 v22, v22
	v_div_fixup_f32 v16, v16, v19, 1.0
	v_mul_f32_e32 v19, v17, v21
	v_fma_f32 v23, -v20, v19, v17
	v_fmac_f32_e32 v19, v23, v21
	v_fma_f32 v17, -v20, v19, v17
	v_add_f32_e32 v20, 1.0, v22
	v_div_scale_f32 v22, s[30:31], v20, v20, 1.0
	v_rcp_f32_e32 v23, v22
	v_div_fmas_f32 v17, v17, v21, v19
	v_div_fixup_f32 v17, v17, v18, 1.0
	v_mul_f32_e32 v18, 0xbfb8aa3b, v29
	v_exp_f32_e32 v18, v18
	v_cvt_pk_bf16_f32 v166, v16, v17
	v_fma_f32 v16, -v22, v23, 1.0
	v_fmac_f32_e32 v23, v16, v23
	v_div_scale_f32 v16, vcc, 1.0, v20, 1.0
	v_mul_f32_e32 v17, v16, v23
	v_fma_f32 v19, -v22, v17, v16
	v_add_f32_e32 v18, 1.0, v18
	v_fmac_f32_e32 v17, v19, v23
	v_div_scale_f32 v19, s[30:31], v18, v18, 1.0
	v_rcp_f32_e32 v21, v19
	v_fma_f32 v16, -v22, v17, v16
	v_div_fmas_f32 v16, v16, v23, v17
	v_mul_f32_e32 v22, 0xbfb8aa3b, v30
	v_fma_f32 v17, -v19, v21, 1.0
	v_fmac_f32_e32 v21, v17, v21
	v_div_scale_f32 v17, vcc, 1.0, v18, 1.0
	v_exp_f32_e32 v22, v22
	v_div_fixup_f32 v16, v16, v20, 1.0
	v_mul_f32_e32 v20, v17, v21
	v_fma_f32 v23, -v19, v20, v17
	v_fmac_f32_e32 v20, v23, v21
	v_fma_f32 v17, -v19, v20, v17
	v_add_f32_e32 v19, 1.0, v22
	v_div_scale_f32 v22, s[30:31], v19, v19, 1.0
	v_rcp_f32_e32 v23, v22
	v_div_fmas_f32 v17, v17, v21, v20
	v_div_fixup_f32 v17, v17, v18, 1.0
	v_mul_f32_e32 v18, 0xbfb8aa3b, v31
	v_exp_f32_e32 v18, v18
	v_cvt_pk_bf16_f32 v167, v16, v17
	v_fma_f32 v16, -v22, v23, 1.0
	v_fmac_f32_e32 v23, v16, v23
	v_div_scale_f32 v16, vcc, 1.0, v19, 1.0
	v_mul_f32_e32 v17, v16, v23
	v_fma_f32 v20, -v22, v17, v16
	v_add_f32_e32 v18, 1.0, v18
	v_fmac_f32_e32 v17, v20, v23
	v_div_scale_f32 v20, s[30:31], v18, v18, 1.0
	v_rcp_f32_e32 v21, v20
	v_fma_f32 v16, -v22, v17, v16
	v_mul_f32_e32 v0, 0xbfb8aa3b, v0
	v_div_fmas_f32 v16, v16, v23, v17
	v_fma_f32 v17, -v20, v21, 1.0
	v_exp_f32_e32 v0, v0
	v_fmac_f32_e32 v21, v17, v21
	v_div_scale_f32 v17, vcc, 1.0, v18, 1.0
	v_div_fixup_f32 v16, v16, v19, 1.0
	v_mul_f32_e32 v19, v17, v21
	v_fma_f32 v22, -v20, v19, v17
	v_fmac_f32_e32 v19, v22, v21
	v_add_f32_e32 v0, 1.0, v0
	v_fma_f32 v17, -v20, v19, v17
	v_div_scale_f32 v20, s[30:31], v0, v0, 1.0
	v_rcp_f32_e32 v22, v20
	v_mul_f32_e32 v1, 0xbfb8aa3b, v1
	v_div_fmas_f32 v17, v17, v21, v19
	v_exp_f32_e32 v1, v1
	v_div_fixup_f32 v17, v17, v18, 1.0
	v_cvt_pk_bf16_f32 v168, v16, v17
	v_fma_f32 v16, -v20, v22, 1.0
	v_fmac_f32_e32 v22, v16, v22
	v_div_scale_f32 v16, vcc, 1.0, v0, 1.0
	v_mul_f32_e32 v17, v16, v22
	v_fma_f32 v18, -v20, v17, v16
	v_add_f32_e32 v1, 1.0, v1
	v_fmac_f32_e32 v17, v18, v22
	v_div_scale_f32 v18, s[30:31], v1, v1, 1.0
	v_rcp_f32_e32 v19, v18
	v_fma_f32 v16, -v20, v17, v16
	v_div_fmas_f32 v16, v16, v22, v17
	v_mul_f32_e32 v2, 0xbfb8aa3b, v2
	v_div_fixup_f32 v0, v16, v0, 1.0
	v_fma_f32 v16, -v18, v19, 1.0
	v_exp_f32_e32 v2, v2
	v_fmac_f32_e32 v19, v16, v19
	v_div_scale_f32 v16, vcc, 1.0, v1, 1.0
	v_mul_f32_e32 v17, v16, v19
	v_fma_f32 v20, -v18, v17, v16
	v_fmac_f32_e32 v17, v20, v19
	v_add_f32_e32 v2, 1.0, v2
	v_fma_f32 v16, -v18, v17, v16
	v_div_scale_f32 v18, s[30:31], v2, v2, 1.0
	v_rcp_f32_e32 v20, v18
	v_mul_f32_e32 v3, 0xbfb8aa3b, v3
	v_div_fmas_f32 v16, v16, v19, v17
	v_exp_f32_e32 v3, v3
	v_div_fixup_f32 v1, v16, v1, 1.0
	v_cvt_pk_bf16_f32 v169, v0, v1
	v_fma_f32 v0, -v18, v20, 1.0
	v_fmac_f32_e32 v20, v0, v20
	v_div_scale_f32 v0, vcc, 1.0, v2, 1.0
	v_mul_f32_e32 v1, v0, v20
	v_fma_f32 v16, -v18, v1, v0
	v_add_f32_e32 v3, 1.0, v3
	v_fmac_f32_e32 v1, v16, v20
	v_div_scale_f32 v16, s[30:31], v3, v3, 1.0
	v_rcp_f32_e32 v17, v16
	v_fma_f32 v0, -v18, v1, v0
	v_mul_f32_e32 v4, 0xbfb8aa3b, v4
	v_div_fmas_f32 v0, v0, v20, v1
; DI unsigned pack2(float a, float b) { unsigned r; asm("v_cvt_pk_bf16_f32 %0, %1, %2" : "=v"(r) : "v"(a), "v"(b)); return r; }
; DI float sigmoidf_(float x) { return 1.f / (1.f + __expf(-x)); }
; DI void merge_phase(const Params& p, int layer, char* lds) {
;     ...
;       const int kw = (br == 0) ? 384 : (br == 1 ? 256 : 128);
;       const int yo = (br == 0) ? 0 : (br == 1 ? 384 : 640);
;       const bf16_t* wu = wl + ((br == 0) ? OW_UA : (br == 1 ? OW_UB : OW_UC));
;       unsigned sg[2][2][8];
;       {
;         f32x16 ag[2][2];
;         zero_acc(ag);
;         gemm_core(hn + (size_t)mt * 256 * 1024, 1024, wl + OW_ING + (size_t)(br * 1024 + nt * 128) * 1024, 1024, 1024, ag, lds);
; #pragma unroll
;         for (int a = 0; a < 2; ++a)
; #pragma unroll
;           for (int c = 0; c < 2; ++c)
; #pragma unroll
;             for (int i = 0; i < 8; ++i) sg[a][c][i] = pack2(sigmoidf_(ag[a][c][2 * i]), sigmoidf_(ag[a][c][2 * i + 1]));
;       }
;       f32x16 au[2][2];
;       zero_acc(au);
;       gemm_core(y + (size_t)mt * 256 * 768 + yo, 768, wu + (size_t)nt * 128 * kw, kw, kw, au, lds);
	v_fma_f32 v1, -v16, v17, 1.0
	v_exp_f32_e32 v4, v4
	v_fmac_f32_e32 v17, v1, v17
	v_div_scale_f32 v1, vcc, 1.0, v3, 1.0
	v_div_fixup_f32 v0, v0, v2, 1.0
	v_mul_f32_e32 v2, v1, v17
	v_fma_f32 v18, -v16, v2, v1
	v_fmac_f32_e32 v2, v18, v17
	v_add_f32_e32 v4, 1.0, v4
	v_fma_f32 v1, -v16, v2, v1
	v_div_scale_f32 v16, s[30:31], v4, v4, 1.0
	v_rcp_f32_e32 v18, v16
	v_div_fmas_f32 v1, v1, v17, v2
	v_mul_f32_e32 v2, 0xbfb8aa3b, v5
	v_exp_f32_e32 v2, v2
	v_div_fixup_f32 v1, v1, v3, 1.0
	v_cvt_pk_bf16_f32 v170, v0, v1
	v_fma_f32 v0, -v16, v18, 1.0
	v_fmac_f32_e32 v18, v0, v18
	v_div_scale_f32 v0, vcc, 1.0, v4, 1.0
	v_mul_f32_e32 v1, v0, v18
	v_fma_f32 v3, -v16, v1, v0
	v_add_f32_e32 v2, 1.0, v2
	v_fmac_f32_e32 v1, v3, v18
	v_div_scale_f32 v3, s[30:31], v2, v2, 1.0
	v_rcp_f32_e32 v5, v3
	v_fma_f32 v0, -v16, v1, v0
	v_div_fmas_f32 v0, v0, v18, v1
	v_mul_f32_e32 v6, 0xbfb8aa3b, v6
	v_fma_f32 v1, -v3, v5, 1.0
	v_fmac_f32_e32 v5, v1, v5
	v_div_scale_f32 v1, vcc, 1.0, v2, 1.0
	v_exp_f32_e32 v6, v6
	v_div_fixup_f32 v0, v0, v4, 1.0
	v_mul_f32_e32 v4, v1, v5
	v_fma_f32 v16, -v3, v4, v1
	v_fmac_f32_e32 v4, v16, v5
	v_fma_f32 v1, -v3, v4, v1
	v_add_f32_e32 v3, 1.0, v6
	v_div_scale_f32 v6, s[30:31], v3, v3, 1.0
	v_rcp_f32_e32 v16, v6
	v_div_fmas_f32 v1, v1, v5, v4
	v_div_fixup_f32 v1, v1, v2, 1.0
	v_mul_f32_e32 v2, 0xbfb8aa3b, v7
	v_exp_f32_e32 v2, v2
	v_cvt_pk_bf16_f32 v171, v0, v1
	v_fma_f32 v0, -v6, v16, 1.0
	v_fmac_f32_e32 v16, v0, v16
	v_div_scale_f32 v0, vcc, 1.0, v3, 1.0
	v_mul_f32_e32 v1, v0, v16
	v_fma_f32 v4, -v6, v1, v0
	v_add_f32_e32 v2, 1.0, v2
	v_fmac_f32_e32 v1, v4, v16
	v_div_scale_f32 v4, s[30:31], v2, v2, 1.0
	v_rcp_f32_e32 v5, v4
	v_fma_f32 v0, -v6, v1, v0
	v_div_fmas_f32 v0, v0, v16, v1
	v_mul_f32_e32 v6, 0xbfb8aa3b, v8
	v_fma_f32 v1, -v4, v5, 1.0
	v_fmac_f32_e32 v5, v1, v5
	v_div_scale_f32 v1, vcc, 1.0, v2, 1.0
	v_exp_f32_e32 v6, v6
	v_div_fixup_f32 v0, v0, v3, 1.0
	v_mul_f32_e32 v3, v1, v5
	v_fma_f32 v7, -v4, v3, v1
	v_fmac_f32_e32 v3, v7, v5
	v_fma_f32 v1, -v4, v3, v1
	v_add_f32_e32 v4, 1.0, v6
	v_div_scale_f32 v6, s[30:31], v4, v4, 1.0
	v_rcp_f32_e32 v7, v6
	v_div_fmas_f32 v1, v1, v5, v3
	v_div_fixup_f32 v1, v1, v2, 1.0
	v_mul_f32_e32 v2, 0xbfb8aa3b, v9
	v_exp_f32_e32 v2, v2
	v_cvt_pk_bf16_f32 v172, v0, v1
	v_fma_f32 v0, -v6, v7, 1.0
	v_fmac_f32_e32 v7, v0, v7
	v_div_scale_f32 v0, vcc, 1.0, v4, 1.0
	v_mul_f32_e32 v1, v0, v7
	v_fma_f32 v3, -v6, v1, v0
	v_add_f32_e32 v2, 1.0, v2
	v_fmac_f32_e32 v1, v3, v7
	v_div_scale_f32 v3, s[30:31], v2, v2, 1.0
	v_rcp_f32_e32 v5, v3
	v_fma_f32 v0, -v6, v1, v0
	v_div_fmas_f32 v0, v0, v7, v1
	v_mul_f32_e32 v6, 0xbfb8aa3b, v10
	v_fma_f32 v1, -v3, v5, 1.0
	v_fmac_f32_e32 v5, v1, v5
	v_div_scale_f32 v1, vcc, 1.0, v2, 1.0
	v_exp_f32_e32 v6, v6
	v_div_fixup_f32 v0, v0, v4, 1.0
	v_mul_f32_e32 v4, v1, v5
	v_fma_f32 v7, -v3, v4, v1
	v_fmac_f32_e32 v4, v7, v5
	v_fma_f32 v1, -v3, v4, v1
	v_add_f32_e32 v3, 1.0, v6
	v_div_scale_f32 v6, s[30:31], v3, v3, 1.0
	v_rcp_f32_e32 v7, v6
	v_div_fmas_f32 v1, v1, v5, v4
	v_div_fixup_f32 v1, v1, v2, 1.0
	v_mul_f32_e32 v2, 0xbfb8aa3b, v11
	v_exp_f32_e32 v2, v2
	v_cvt_pk_bf16_f32 v173, v0, v1
	v_fma_f32 v0, -v6, v7, 1.0
	v_fmac_f32_e32 v7, v0, v7
	v_div_scale_f32 v0, vcc, 1.0, v3, 1.0
	v_mul_f32_e32 v1, v0, v7
	v_fma_f32 v4, -v6, v1, v0
	v_add_f32_e32 v2, 1.0, v2
	v_fmac_f32_e32 v1, v4, v7
	v_div_scale_f32 v4, s[30:31], v2, v2, 1.0
	v_rcp_f32_e32 v5, v4
	v_fma_f32 v0, -v6, v1, v0
	v_div_fmas_f32 v0, v0, v7, v1
	v_mul_f32_e32 v6, 0xbfb8aa3b, v12
	v_fma_f32 v1, -v4, v5, 1.0
	v_fmac_f32_e32 v5, v1, v5
	v_div_scale_f32 v1, vcc, 1.0, v2, 1.0
	v_exp_f32_e32 v6, v6
	v_div_fixup_f32 v0, v0, v3, 1.0
	v_mul_f32_e32 v3, v1, v5
	v_fma_f32 v7, -v4, v3, v1
	v_fmac_f32_e32 v3, v7, v5
	v_fma_f32 v1, -v4, v3, v1
	v_add_f32_e32 v4, 1.0, v6
	v_div_scale_f32 v6, s[30:31], v4, v4, 1.0
	v_rcp_f32_e32 v7, v6
	v_div_fmas_f32 v1, v1, v5, v3
	v_div_fixup_f32 v1, v1, v2, 1.0
	v_mul_f32_e32 v2, 0xbfb8aa3b, v13
	v_exp_f32_e32 v2, v2
	v_cvt_pk_bf16_f32 v174, v0, v1
	v_fma_f32 v0, -v6, v7, 1.0
	v_fmac_f32_e32 v7, v0, v7
	v_div_scale_f32 v0, vcc, 1.0, v4, 1.0
	v_mul_f32_e32 v1, v0, v7
	v_fma_f32 v3, -v6, v1, v0
	v_add_f32_e32 v2, 1.0, v2
	v_fmac_f32_e32 v1, v3, v7
	v_div_scale_f32 v3, s[30:31], v2, v2, 1.0
	v_rcp_f32_e32 v5, v3
	v_fma_f32 v0, -v6, v1, v0
	v_div_fmas_f32 v0, v0, v7, v1
	v_mul_f32_e32 v6, 0xbfb8aa3b, v14
	v_fma_f32 v1, -v3, v5, 1.0
	v_fmac_f32_e32 v5, v1, v5
	v_div_scale_f32 v1, vcc, 1.0, v2, 1.0
	v_exp_f32_e32 v6, v6
	v_div_fixup_f32 v0, v0, v4, 1.0
	v_mul_f32_e32 v4, v1, v5
	v_fma_f32 v7, -v3, v4, v1
	v_fmac_f32_e32 v4, v7, v5
	v_fma_f32 v1, -v3, v4, v1
	v_add_f32_e32 v3, 1.0, v6
	v_div_scale_f32 v6, s[30:31], v3, v3, 1.0
	v_rcp_f32_e32 v7, v6
	v_div_fmas_f32 v1, v1, v5, v4
	v_div_fixup_f32 v1, v1, v2, 1.0
	v_mul_f32_e32 v2, 0xbfb8aa3b, v15
	v_exp_f32_e32 v2, v2
	v_cvt_pk_bf16_f32 v175, v0, v1
	v_fma_f32 v0, -v6, v7, 1.0
	v_fmac_f32_e32 v7, v0, v7
	v_div_scale_f32 v0, vcc, 1.0, v3, 1.0
	v_mul_f32_e32 v1, v0, v7
	v_fma_f32 v4, -v6, v1, v0
	v_add_f32_e32 v2, 1.0, v2
	v_fmac_f32_e32 v1, v4, v7
	v_div_scale_f32 v4, s[30:31], v2, v2, 1.0
	v_rcp_f32_e32 v5, v4
	v_fma_f32 v0, -v6, v1, v0
	v_div_fmas_f32 v0, v0, v7, v1
	v_div_fixup_f32 v0, v0, v3, 1.0
	v_fma_f32 v1, -v4, v5, 1.0
	v_fmac_f32_e32 v5, v1, v5
	v_div_scale_f32 v1, vcc, 1.0, v2, 1.0
	v_mul_f32_e32 v3, v1, v5
	v_fma_f32 v6, -v4, v3, v1
	v_fmac_f32_e32 v3, v6, v5
	s_cselect_b32 s27, 0x17b0000, s65
	v_fma_f32 v1, -v4, v3, v1
	s_cselect_b32 s64, 0x180, s64
	s_cselect_b32 s26, 0, s26
	s_lshl_b32 s65, s27, 1
	v_div_fmas_f32 v1, v1, v5, v3
	s_add_u32 vcc_lo, s4, s65
	v_div_fixup_f32 v1, v1, v2, 1.0
	s_addc_u32 vcc_hi, s22, 0
	s_lshl_b32 s24, s26, 1
	v_cvt_pk_bf16_f32 v176, v0, v1
	s_add_u32 s26, s9, s24
	s_mul_i32 s25, s57, s64
	s_mul_hi_u32 s30, s56, s64
	v_mov_b32_e32 v1, v129
	s_nop 15
	s_nop 15
	s_nop 7
	s_barrier
; #define TIDX get_tid_()
; #define GEMM_ISSUE(kt_, st_) do { char* sb_ = lw + (st_) * STAGE_B; const char* ak_ = Ab + (size_t)(kt_) * 128; const char* bk_ = Bb + (size_t)(kt_) * 128; \
;     _Pragma("unroll") for (int i_ = 0; i_ < 4; ++i_) glds16(ak_ + avo[i_], sb_ + i_ * 8192); \
;     _Pragma("unroll") for (int i_ = 0; i_ < 2; ++i_) glds16(bk_ + bvo[i_], sb_ + 32768 + i_ * 8192); } while (0)
;   const int tid = TIDX, lane = tid & 63, wid = tid >> 6, wr = wid >> 1, wc = wid & 1, r = lane & 31, h = lane >> 5;
;   const int ch = (tid & 7) ^ ((tid >> 4) & 7);
;   unsigned avo[4], bvo[2];
; #pragma unroll
;   for (int i = 0; i < 4; ++i) avo[i] = (unsigned)(((tid >> 3) + 64 * i) * lda * 2 + ch * 16);
; #pragma unroll
;   for (int i = 0; i < 2; ++i) bvo[i] = (unsigned)(((tid >> 3) + 64 * i) * ldb * 2 + ch * 16);
;   const char* Ab = (const char*)A; const char* Bb = (const char*)Bt;
;   char* lw = lds + tid * 16;
;   const int nk = K >> 6;
;   const unsigned swz = (unsigned)((r >> 1) & 7);
;   const unsigned arow_u = (unsigned)((wr * 64 + r) * 128), brow_u = (unsigned)((wc * 64 + r) * 128);
;   const unsigned co0 = ((0u + h) ^ swz) << 4, co1 = ((2u + h) ^ swz) << 4, co2 = ((4u + h) ^ swz) << 4, co3 = ((6u + h) ^ swz) << 4;
;     ...
;   if (PART != 2) {
;     GEMM_ISSUE(0, 0);
;     if (nk > 1) GEMM_ISSUE(1, 1);
;   }
; DI void merge_phase(const Params& p, int layer, char* lds) {
;     ...
;       f32x16 au[2][2];
;       zero_acc(au);
;       gemm_core(y + (size_t)mt * 256 * 768 + yo, 768, wu + (size_t)nt * 128 * kw, kw, kw, au, lds);
	s_addc_u32 s27, s15, 0
	s_add_i32 s31, s30, s25
	s_movk_i32 s25, 0x70
	v_lshlrev_b32_e32 v5, 4, v1
	v_ashrrev_i32_e32 v22, 3, v1
	v_bitop3_b32 v23, v5, s25, v1 bitop3:0x48
	s_movk_i32 s25, 0x600
	v_lshrrev_b32_e32 v3, 5, v1
	v_mul_lo_u32 v0, v22, s25
	v_and_b32_e32 v7, 31, v1
	v_add_u32_e32 v177, 0, v5
	v_lshrrev_b32_e32 v5, 1, v1
	v_bfe_u32 v10, v1, 1, 3
	s_mov_b32 s25, 0x1ffffc0
	v_and_or_b32 v7, v5, s25, v7
	v_bitop3_b32 v18, v3, v10, 1 bitop3:0x6c
	v_readfirstlane_b32 s25, v177
	v_add_u32_e32 v3, 0x2000, v177
	s_mul_i32 s30, s56, s64
	v_or_b32_e32 v130, v23, v0
	v_mul_lo_u32 v6, s64, v22
	v_bfe_u32 v9, v1, 5, 1
	s_mov_b32 m0, s25
	v_readfirstlane_b32 s25, v3
	v_add_u32_e32 v5, 0x4000, v177
	s_lshl_b64 s[30:31], s[30:31], 1
	v_add_u32_e32 v0, 0x18000, v130
	v_lshlrev_b32_e32 v8, 1, v6
	v_bitop3_b32 v25, v9, v10, 2 bitop3:0x36
	v_bitop3_b32 v19, v9, v10, 4 bitop3:0x36
	v_bitop3_b32 v26, v9, v10, 6 bitop3:0x36
	global_load_lds_dwordx4 v130, s[26:27]
	s_mov_b32 m0, s25
	v_readfirstlane_b32 s25, v5
	v_add_u32_e32 v9, 0x6000, v177
	s_add_u32 s30, vcc_lo, s30
	v_add_u32_e32 v2, 0x30000, v130
	v_or_b32_e32 v6, v23, v8
	v_lshl_add_u32 v8, s64, 7, v8
	global_load_lds_dwordx4 v0, s[26:27]
	s_mov_b32 m0, s25
	v_readfirstlane_b32 s25, v9
	v_add_u32_e32 v9, 0x8000, v177
	s_addc_u32 s31, vcc_hi, s31
	v_or_b32_e32 v8, v8, v23
	global_load_lds_dwordx4 v2, s[26:27]
	s_mov_b32 m0, s25
	v_readfirstlane_b32 s25, v9
	v_mov_b32_e32 v9, v131
	v_add_u32_e32 v4, 0x48000, v130
	v_lshl_add_u64 v[20:21], s[30:31], 0, v[8:9]
	v_add_u32_e32 v9, 0xa000, v177
	global_load_lds_dwordx4 v4, s[26:27]
	s_mov_b32 m0, s25
	v_readfirstlane_b32 s25, v9
	v_lshl_add_u64 v[10:11], s[26:27], 0, v[130:131]
	global_load_lds_dwordx4 v6, s[30:31]
	s_mov_b32 m0, s25
	v_lshlrev_b32_e32 v181, 4, v25
	v_add_u32_e32 v25, 0xc000, v177
	v_lshlrev_b32_e32 v24, 7, v1
	v_mov_b32_e32 v1, v131
	global_load_lds_dwordx4 v8, s[30:31]
	v_lshl_add_u64 v[8:9], v[10:11], 0, s[92:93]
	v_readfirstlane_b32 s25, v25
	v_add_u32_e32 v10, 0xe000, v177
	v_lshl_add_u64 v[12:13], s[26:27], 0, v[0:1]
	v_mov_b32_e32 v3, v131
	s_mov_b32 m0, s25
	v_readfirstlane_b32 s25, v10
	v_add_u32_e32 v10, 0x10000, v177
	v_lshl_add_u64 v[14:15], s[26:27], 0, v[2:3]
	v_mov_b32_e32 v5, v131
	global_load_lds_dwordx4 v[8:9], off
	v_lshl_add_u64 v[8:9], v[12:13], 0, s[92:93]
	s_mov_b32 m0, s25
	v_readfirstlane_b32 s25, v10
	v_add_u32_e32 v10, 0x12000, v177
	v_lshl_add_u64 v[16:17], s[26:27], 0, v[4:5]
	v_lshlrev_b32_e32 v180, 7, v7
	v_mov_b32_e32 v7, v131
	global_load_lds_dwordx4 v[8:9], off
	v_lshl_add_u64 v[8:9], v[14:15], 0, s[92:93]
	s_mov_b32 m0, s25
	v_readfirstlane_b32 s25, v10
	v_add_u32_e32 v10, 0x14000, v177
	v_lshlrev_b32_e32 v179, 4, v18
	v_lshlrev_b32_e32 v178, 4, v19
	v_lshl_add_u64 v[18:19], s[30:31], 0, v[6:7]
	global_load_lds_dwordx4 v[8:9], off
	v_lshl_add_u64 v[8:9], v[16:17], 0, s[92:93]
	s_mov_b32 m0, s25
	v_readfirstlane_b32 s25, v10
	v_add_u32_e32 v10, 0x16000, v177
	global_load_lds_dwordx4 v[8:9], off
	v_lshl_add_u64 v[8:9], v[18:19], 0, s[92:93]
	s_mov_b32 m0, s25
	v_readfirstlane_b32 s25, v10
	global_load_lds_dwordx4 v[8:9], off
	v_lshl_add_u64 v[8:9], v[20:21], 0, s[92:93]
	s_mov_b32 m0, s25
	s_lshr_b32 s26, s64, 6
	global_load_lds_dwordx4 v[8:9], off
	s_add_u32 s30, s69, s24
	s_mul_i32 s24, s61, s64
	s_mul_hi_u32 s25, s60, s64
	s_addc_u32 s31, s70, 0
	s_add_i32 s25, s25, s24
	s_mul_i32 s24, s60, s64
	s_add_u32 s24, s67, s24
	v_lshl_add_u64 v[134:135], s[30:31], 0, v[0:1]
	s_addc_u32 s25, s23, s25
	v_lshl_add_u32 v0, v22, 1, v196
	v_lshl_add_u64 v[132:133], s[30:31], 0, v[130:131]
	v_lshl_add_u64 v[136:137], s[30:31], 0, v[2:3]
	v_lshl_add_u64 v[138:139], s[30:31], 0, v[4:5]
	s_add_u32 s30, s24, s65
	v_mul_lo_u32 v0, s64, v0
	s_addc_u32 s31, s25, 0
	v_or_b32_e32 v130, v0, v23
	v_mov_b32_e32 v0, 0
	s_mov_b32 s63, 0
	s_mov_b32 s71, 1
	v_and_b32_e32 v182, 0x2f80, v24
	v_lshlrev_b32_e32 v183, 4, v26
	v_lshl_add_u64 v[140:141], s[30:31], 0, v[6:7]
	v_lshl_add_u64 v[142:143], s[30:31], 0, v[130:131]
	v_mov_b32_e32 v1, v0
	v_mov_b32_e32 v2, v0
	v_mov_b32_e32 v3, v0
	v_mov_b32_e32 v4, v0
	v_mov_b32_e32 v5, v0
	v_mov_b32_e32 v6, v0
	v_mov_b32_e32 v7, v0
	v_mov_b32_e32 v8, v0
	v_mov_b32_e32 v9, v0
	v_mov_b32_e32 v10, v0
	v_mov_b32_e32 v11, v0
	v_mov_b32_e32 v12, v0
	v_mov_b32_e32 v13, v0
	v_mov_b32_e32 v14, v0
	v_mov_b32_e32 v15, v0
	v_mov_b32_e32 v16, v0
	v_mov_b32_e32 v17, v0
	v_mov_b32_e32 v18, v0
	v_mov_b32_e32 v19, v0
	v_mov_b32_e32 v20, v0
	v_mov_b32_e32 v21, v0
	v_mov_b32_e32 v22, v0
	v_mov_b32_e32 v23, v0
	v_mov_b32_e32 v24, v0
	v_mov_b32_e32 v25, v0
	v_mov_b32_e32 v26, v0
	v_mov_b32_e32 v27, v0
	v_mov_b32_e32 v28, v0
	v_mov_b32_e32 v29, v0
	v_mov_b32_e32 v30, v0
	v_mov_b32_e32 v31, v0
	v_mov_b32_e32 v32, v0
	v_mov_b32_e32 v33, v0
	v_mov_b32_e32 v34, v0
	v_mov_b32_e32 v35, v0
	v_mov_b32_e32 v36, v0
	v_mov_b32_e32 v37, v0
	v_mov_b32_e32 v38, v0
	v_mov_b32_e32 v39, v0
	v_mov_b32_e32 v40, v0
	v_mov_b32_e32 v41, v0
	v_mov_b32_e32 v42, v0
	v_mov_b32_e32 v43, v0
	v_mov_b32_e32 v44, v0
	v_mov_b32_e32 v45, v0
	v_mov_b32_e32 v46, v0
	v_mov_b32_e32 v47, v0
	v_mov_b32_e32 v48, v0
	v_mov_b32_e32 v49, v0
	v_mov_b32_e32 v50, v0
	v_mov_b32_e32 v51, v0
	v_mov_b32_e32 v52, v0
	v_mov_b32_e32 v53, v0
	v_mov_b32_e32 v54, v0
	v_mov_b32_e32 v55, v0
	v_mov_b32_e32 v56, v0
	v_mov_b32_e32 v57, v0
	v_mov_b32_e32 v58, v0
	v_mov_b32_e32 v59, v0
	v_mov_b32_e32 v60, v0
	v_mov_b32_e32 v61, v0
	v_mov_b32_e32 v62, v0
	v_mov_b32_e32 v63, v0
	s_branch .LBB0_109
